# quarter-mode tail units run a separate copy of the K-loop; the main K-loops carry no mode branches
# speedup vs baseline: 1.0160x; 1.0160x over previous
.LBB0_1435:
	s_ashr_i32 s27, s26, 31
	s_lshl_b64 s[28:29], s[26:27], 19
	s_add_u32 s28, s42, s28
	s_addc_u32 s29, s43, s29
	s_and_b64 s[30:31], s[6:7], exec
	s_cselect_b32 s9, s29, s37
	s_cselect_b32 s27, s28, s36
	s_ashr_i32 s25, s24, 31
	s_lshl_b64 s[30:31], s[24:25], 19
	s_add_u32 s30, s44, s30
	s_addc_u32 s31, s45, s31
	s_and_b64 s[40:41], s[6:7], exec
	s_cselect_b32 s25, s31, s39
	s_cselect_b32 s65, s30, s38
	s_add_u32 s36, s36, 0x40080
	s_addc_u32 s37, s37, 0
	s_add_u32 s66, s38, 0x100
	v_mov_b32_e32 v0, 0
	s_addc_u32 s67, s39, 0
	s_mov_b32 s68, -2
	s_waitcnt lgkmcnt(0)
	v_mov_b32_e32 v1, v0
	v_mov_b32_e32 v2, v0
	v_mov_b32_e32 v3, v0
	v_mov_b32_e32 v4, v0
	v_mov_b32_e32 v5, v0
	v_mov_b32_e32 v6, v0
	v_mov_b32_e32 v7, v0
	v_mov_b32_e32 v16, v0
	v_mov_b32_e32 v17, v0
	v_mov_b32_e32 v18, v0
	v_mov_b32_e32 v19, v0
	v_mov_b32_e32 v20, v0
	v_mov_b32_e32 v21, v0
	v_mov_b32_e32 v22, v0
	v_mov_b32_e32 v23, v0
	v_mov_b32_e32 v32, v0
	v_mov_b32_e32 v33, v0
	v_mov_b32_e32 v34, v0
	v_mov_b32_e32 v35, v0
	v_mov_b32_e32 v36, v0
	v_mov_b32_e32 v37, v0
	v_mov_b32_e32 v38, v0
	v_mov_b32_e32 v39, v0
	v_mov_b32_e32 v48, v0
	v_mov_b32_e32 v49, v0
	v_mov_b32_e32 v50, v0
	v_mov_b32_e32 v51, v0
	v_mov_b32_e32 v52, v0
	v_mov_b32_e32 v53, v0
	v_mov_b32_e32 v54, v0
	v_mov_b32_e32 v55, v0
	v_mov_b32_e32 v8, v0
	v_mov_b32_e32 v9, v0
	v_mov_b32_e32 v10, v0
	v_mov_b32_e32 v11, v0
	v_mov_b32_e32 v12, v0
	v_mov_b32_e32 v13, v0
	v_mov_b32_e32 v14, v0
	v_mov_b32_e32 v15, v0
	v_mov_b32_e32 v24, v0
	v_mov_b32_e32 v25, v0
	v_mov_b32_e32 v26, v0
	v_mov_b32_e32 v27, v0
	v_mov_b32_e32 v28, v0
	v_mov_b32_e32 v29, v0
	v_mov_b32_e32 v30, v0
	v_mov_b32_e32 v31, v0
	v_mov_b32_e32 v40, v0
	v_mov_b32_e32 v41, v0
	v_mov_b32_e32 v42, v0
	v_mov_b32_e32 v43, v0
	v_mov_b32_e32 v44, v0
	v_mov_b32_e32 v45, v0
	v_mov_b32_e32 v46, v0
	v_mov_b32_e32 v47, v0
	v_mov_b32_e32 v56, v0
	v_mov_b32_e32 v57, v0
	v_mov_b32_e32 v58, v0
	v_mov_b32_e32 v59, v0
	v_mov_b32_e32 v60, v0
	v_mov_b32_e32 v61, v0
	v_mov_b32_e32 v62, v0
	v_mov_b32_e32 v63, v0
	v_mov_b32_e32 v64, v0
	v_mov_b32_e32 v65, v0
	v_mov_b32_e32 v66, v0
	v_mov_b32_e32 v67, v0
	v_mov_b32_e32 v68, v0
	v_mov_b32_e32 v69, v0
	v_mov_b32_e32 v70, v0
	v_mov_b32_e32 v71, v0
	v_mov_b32_e32 v80, v0
	v_mov_b32_e32 v81, v0
	v_mov_b32_e32 v82, v0
	v_mov_b32_e32 v83, v0
	v_mov_b32_e32 v84, v0
	v_mov_b32_e32 v85, v0
	v_mov_b32_e32 v86, v0
	v_mov_b32_e32 v87, v0
	v_mov_b32_e32 v96, v0
	v_mov_b32_e32 v97, v0
	v_mov_b32_e32 v98, v0
	v_mov_b32_e32 v99, v0
	v_mov_b32_e32 v100, v0
	v_mov_b32_e32 v101, v0
	v_mov_b32_e32 v102, v0
	v_mov_b32_e32 v103, v0
	v_mov_b32_e32 v112, v0
	v_mov_b32_e32 v113, v0
	v_mov_b32_e32 v114, v0
	v_mov_b32_e32 v115, v0
	v_mov_b32_e32 v116, v0
	v_mov_b32_e32 v117, v0
	v_mov_b32_e32 v118, v0
	v_mov_b32_e32 v119, v0
	v_mov_b32_e32 v72, v0
	v_mov_b32_e32 v73, v0
	v_mov_b32_e32 v74, v0
	v_mov_b32_e32 v75, v0
	v_mov_b32_e32 v76, v0
	v_mov_b32_e32 v77, v0
	v_mov_b32_e32 v78, v0
	v_mov_b32_e32 v79, v0
	v_mov_b32_e32 v88, v0
	v_mov_b32_e32 v89, v0
	v_mov_b32_e32 v90, v0
	v_mov_b32_e32 v91, v0
	v_mov_b32_e32 v92, v0
	v_mov_b32_e32 v93, v0
	v_mov_b32_e32 v94, v0
	v_mov_b32_e32 v95, v0
	v_mov_b32_e32 v104, v0
	v_mov_b32_e32 v105, v0
	v_mov_b32_e32 v106, v0
	v_mov_b32_e32 v107, v0
	v_mov_b32_e32 v108, v0
	v_mov_b32_e32 v109, v0
	v_mov_b32_e32 v110, v0
	v_mov_b32_e32 v111, v0
	v_mov_b32_e32 v120, v0
	v_mov_b32_e32 v121, v0
	v_mov_b32_e32 v122, v0
	v_mov_b32_e32 v123, v0
	v_mov_b32_e32 v124, v0
	v_mov_b32_e32 v125, v0
	v_mov_b32_e32 v126, v0
	v_mov_b32_e32 v127, v0
	s_branch .Lqk_skip_6

.Lmm_6_7:
	s_setprio 0
	s_barrier
	s_add_i32 s68, s68, 2
	s_add_u32 s36, s36, 0x100
	s_addc_u32 s37, s37, 0
	s_add_u32 s66, s66, 0x100
	s_addc_u32 s67, s67, 0
	s_cmp_gt_u32 s68, 13
	s_cbranch_scc0 .Lqk_6
	s_branch .Lqk_join_6

.LBB0_1436:
	ds_read_b128 v[128:131], v165
	ds_read_b128 v[132:135], v165 offset:1024
	ds_read_b128 v[136:139], v165 offset:2048
	ds_read_b128 v[140:143], v165 offset:3072
	ds_read_b128 v[156:159], v166
	ds_read_b128 v[160:163], v166 offset:1024
	ds_read_b128 v[170:173], v166 offset:2048
	ds_read_b128 v[174:177], v166 offset:3072
	s_add_u32 s38, s36, 0xfffc0080
	s_addc_u32 s39, s37, -1
	s_cmp_eq_u32 s68, 12
	s_cselect_b32 s41, s9, s39
	s_cselect_b32 s40, s27, s38
	s_cselect_b32 s39, s25, s67
	s_cselect_b32 s38, s65, s66
	v_lshl_add_u64 v[178:179], s[36:37], 0, v[148:149]
	s_add_i32 m0, s35, 0xc000
	ds_read_b128 v[182:185], v167
	ds_read_b128 v[186:189], v167 offset:1024
	ds_read_b128 v[190:193], v167 offset:2048
	ds_read_b128 v[194:197], v167 offset:3072
	ds_read_b128 v[198:201], v167 offset:4096
	ds_read_b128 v[202:205], v167 offset:5120
	ds_read_b128 v[206:209], v167 offset:6144
	ds_read_b128 v[210:213], v167 offset:7168
	global_load_lds_dwordx4 v[178:179], off
	v_lshl_add_u64 v[178:179], s[36:37], 0, v[150:151]
	s_add_i32 m0, s35, 0xe000
	s_nop 0
	global_load_lds_dwordx4 v[178:179], off
	s_waitcnt vmcnt(8)
	s_waitcnt lgkmcnt(0)
	s_barrier
	s_setprio 1
	s_waitcnt lgkmcnt(0)
	v_mfma_f32_16x16x32_bf16 v[124:127], v[128:131], v[182:185], v[124:127]
	v_mfma_f32_16x16x32_bf16 v[120:123], v[136:139], v[182:185], v[120:123]
	v_mfma_f32_16x16x32_bf16 v[108:111], v[128:131], v[190:193], v[108:111]
	v_mfma_f32_16x16x32_bf16 v[104:107], v[136:139], v[190:193], v[104:107]
	v_mfma_f32_16x16x32_bf16 v[92:95], v[128:131], v[198:201], v[92:95]
	v_mfma_f32_16x16x32_bf16 v[88:91], v[136:139], v[198:201], v[88:91]
	v_mfma_f32_16x16x32_bf16 v[76:79], v[128:131], v[206:209], v[76:79]
	v_mfma_f32_16x16x32_bf16 v[72:75], v[136:139], v[206:209], v[72:75]
	v_mfma_f32_16x16x32_bf16 v[124:127], v[132:135], v[186:189], v[124:127]
	v_mfma_f32_16x16x32_bf16 v[120:123], v[140:143], v[186:189], v[120:123]
	v_mfma_f32_16x16x32_bf16 v[108:111], v[132:135], v[194:197], v[108:111]
	v_mfma_f32_16x16x32_bf16 v[104:107], v[140:143], v[194:197], v[104:107]
	v_mfma_f32_16x16x32_bf16 v[92:95], v[132:135], v[202:205], v[92:95]
	v_mfma_f32_16x16x32_bf16 v[88:91], v[140:143], v[202:205], v[88:91]
	v_mfma_f32_16x16x32_bf16 v[76:79], v[132:135], v[210:213], v[76:79]
	v_mfma_f32_16x16x32_bf16 v[72:75], v[140:143], v[210:213], v[72:75]
	s_setprio 0
	s_setprio 1
	v_mfma_f32_16x16x32_bf16 v[116:119], v[156:159], v[182:185], v[116:119]
	v_mfma_f32_16x16x32_bf16 v[112:115], v[170:173], v[182:185], v[112:115]
	v_mfma_f32_16x16x32_bf16 v[100:103], v[156:159], v[190:193], v[100:103]
	v_mfma_f32_16x16x32_bf16 v[96:99], v[170:173], v[190:193], v[96:99]
	v_mfma_f32_16x16x32_bf16 v[84:87], v[156:159], v[198:201], v[84:87]
	v_mfma_f32_16x16x32_bf16 v[80:83], v[170:173], v[198:201], v[80:83]
	v_mfma_f32_16x16x32_bf16 v[68:71], v[156:159], v[206:209], v[68:71]
	v_mfma_f32_16x16x32_bf16 v[64:67], v[170:173], v[206:209], v[64:67]
	v_mfma_f32_16x16x32_bf16 v[116:119], v[160:163], v[186:189], v[116:119]
	v_mfma_f32_16x16x32_bf16 v[112:115], v[174:177], v[186:189], v[112:115]
	v_mfma_f32_16x16x32_bf16 v[100:103], v[160:163], v[194:197], v[100:103]
	v_mfma_f32_16x16x32_bf16 v[96:99], v[174:177], v[194:197], v[96:99]
	v_mfma_f32_16x16x32_bf16 v[84:87], v[160:163], v[202:205], v[84:87]
	v_mfma_f32_16x16x32_bf16 v[80:83], v[174:177], v[202:205], v[80:83]
	v_mfma_f32_16x16x32_bf16 v[68:71], v[160:163], v[210:213], v[68:71]
	v_mfma_f32_16x16x32_bf16 v[64:67], v[174:177], v[210:213], v[64:67]
	s_setprio 0
	s_barrier
	s_add_i32 s69, s58, s48
	v_lshl_add_u64 v[178:179], s[38:39], 0, v[144:145]
	s_mov_b32 m0, s69
	ds_read_b128 v[182:185], v167 offset:16384
	ds_read_b128 v[186:189], v167 offset:17408
	ds_read_b128 v[190:193], v167 offset:18432
	ds_read_b128 v[194:197], v167 offset:19456
	ds_read_b128 v[198:201], v167 offset:20480
	ds_read_b128 v[202:205], v167 offset:21504
	ds_read_b128 v[206:209], v167 offset:22528
	ds_read_b128 v[210:213], v167 offset:23552
	global_load_lds_dwordx4 v[178:179], off
	s_add_i32 m0, s69, 0x2000
	s_add_u32 s70, s38, 0x40000
	v_lshl_add_u64 v[214:215], s[38:39], 0, v[146:147]
	s_addc_u32 s71, s39, 0
	s_add_i32 s69, s59, s48
	global_load_lds_dwordx4 v[214:215], off
	v_lshl_add_u64 v[216:217], s[70:71], 0, v[144:145]
	s_mov_b32 m0, s69
	v_lshl_add_u64 v[218:219], s[40:41], 0, v[146:147]
	global_load_lds_dwordx4 v[216:217], off
	v_lshl_add_u64 v[216:217], s[70:71], 0, v[146:147]
	s_add_i32 m0, s69, 0x2000
	s_nop 0
	global_load_lds_dwordx4 v[216:217], off
	v_lshl_add_u64 v[216:217], s[40:41], 0, v[144:145]
	s_mov_b32 m0, s35
	s_nop 0
	global_load_lds_dwordx4 v[216:217], off
	s_mov_b32 m0, s49
	s_nop 0
	global_load_lds_dwordx4 v[218:219], off
	s_waitcnt vmcnt(8)
	s_waitcnt lgkmcnt(0)
	s_barrier
	s_setprio 1
	s_waitcnt lgkmcnt(0)
	v_mfma_f32_16x16x32_bf16 v[60:63], v[128:131], v[182:185], v[60:63]
	v_mfma_f32_16x16x32_bf16 v[56:59], v[136:139], v[182:185], v[56:59]
	v_mfma_f32_16x16x32_bf16 v[44:47], v[128:131], v[190:193], v[44:47]
	v_mfma_f32_16x16x32_bf16 v[40:43], v[136:139], v[190:193], v[40:43]
	v_mfma_f32_16x16x32_bf16 v[28:31], v[128:131], v[198:201], v[28:31]
	v_mfma_f32_16x16x32_bf16 v[24:27], v[136:139], v[198:201], v[24:27]
	v_mfma_f32_16x16x32_bf16 v[12:15], v[128:131], v[206:209], v[12:15]
	v_mfma_f32_16x16x32_bf16 v[8:11], v[136:139], v[206:209], v[8:11]
	v_mfma_f32_16x16x32_bf16 v[60:63], v[132:135], v[186:189], v[60:63]
	v_mfma_f32_16x16x32_bf16 v[56:59], v[140:143], v[186:189], v[56:59]
	v_mfma_f32_16x16x32_bf16 v[44:47], v[132:135], v[194:197], v[44:47]
	v_mfma_f32_16x16x32_bf16 v[40:43], v[140:143], v[194:197], v[40:43]
	v_mfma_f32_16x16x32_bf16 v[28:31], v[132:135], v[202:205], v[28:31]
	v_mfma_f32_16x16x32_bf16 v[24:27], v[140:143], v[202:205], v[24:27]
	v_mfma_f32_16x16x32_bf16 v[12:15], v[132:135], v[210:213], v[12:15]
	v_mfma_f32_16x16x32_bf16 v[8:11], v[140:143], v[210:213], v[8:11]
	s_setprio 0
	s_setprio 1
	v_mfma_f32_16x16x32_bf16 v[52:55], v[156:159], v[182:185], v[52:55]
	v_mfma_f32_16x16x32_bf16 v[48:51], v[170:173], v[182:185], v[48:51]
	v_mfma_f32_16x16x32_bf16 v[36:39], v[156:159], v[190:193], v[36:39]
	v_mfma_f32_16x16x32_bf16 v[32:35], v[170:173], v[190:193], v[32:35]
	v_mfma_f32_16x16x32_bf16 v[20:23], v[156:159], v[198:201], v[20:23]
	v_mfma_f32_16x16x32_bf16 v[16:19], v[170:173], v[198:201], v[16:19]
	v_mfma_f32_16x16x32_bf16 v[4:7], v[156:159], v[206:209], v[4:7]
	v_mfma_f32_16x16x32_bf16 v[0:3], v[170:173], v[206:209], v[0:3]
	v_mfma_f32_16x16x32_bf16 v[52:55], v[160:163], v[186:189], v[52:55]
	v_mfma_f32_16x16x32_bf16 v[48:51], v[174:177], v[186:189], v[48:51]
	v_mfma_f32_16x16x32_bf16 v[36:39], v[160:163], v[194:197], v[36:39]
	v_mfma_f32_16x16x32_bf16 v[32:35], v[174:177], v[194:197], v[32:35]
	v_mfma_f32_16x16x32_bf16 v[20:23], v[160:163], v[202:205], v[20:23]
	v_mfma_f32_16x16x32_bf16 v[16:19], v[174:177], v[202:205], v[16:19]
	v_mfma_f32_16x16x32_bf16 v[4:7], v[160:163], v[210:213], v[4:7]
	v_mfma_f32_16x16x32_bf16 v[0:3], v[174:177], v[210:213], v[0:3]
	s_setprio 0
	s_barrier
	s_add_i32 s69, 0, 0x18000
	s_add_i32 s70, 0, 0x1c000
	v_add_u32_e32 v140, s69, v164
	v_add_u32_e32 v169, s70, v164
	ds_read_b128 v[128:131], v140
	ds_read_b128 v[132:135], v140 offset:1024
	ds_read_b128 v[136:139], v140 offset:2048
	ds_read_b128 v[140:143], v140 offset:3072
	ds_read_b128 v[156:159], v169
	ds_read_b128 v[160:163], v169 offset:1024
	ds_read_b128 v[170:173], v169 offset:2048
	ds_read_b128 v[174:177], v169 offset:3072
	s_add_u32 s40, s40, 0x40000
	s_addc_u32 s41, s41, 0
	s_mov_b32 m0, s50
	v_lshl_add_u64 v[220:221], s[40:41], 0, v[144:145]
	ds_read_b128 v[182:185], v167 offset:32768
	ds_read_b128 v[186:189], v167 offset:33792
	ds_read_b128 v[190:193], v167 offset:34816
	ds_read_b128 v[194:197], v167 offset:35840
	ds_read_b128 v[198:201], v167 offset:36864
	ds_read_b128 v[202:205], v167 offset:37888
	ds_read_b128 v[206:209], v167 offset:38912
	ds_read_b128 v[210:213], v167 offset:39936
	global_load_lds_dwordx4 v[220:221], off
	v_lshl_add_u64 v[220:221], s[40:41], 0, v[146:147]
	s_mov_b32 m0, s51
	s_nop 0
	global_load_lds_dwordx4 v[220:221], off
	s_waitcnt vmcnt(8)
	s_waitcnt lgkmcnt(0)
	s_barrier
	s_setprio 1
	s_waitcnt lgkmcnt(0)
	v_mfma_f32_16x16x32_bf16 v[124:127], v[128:131], v[182:185], v[124:127]
	v_mfma_f32_16x16x32_bf16 v[120:123], v[136:139], v[182:185], v[120:123]
	v_mfma_f32_16x16x32_bf16 v[108:111], v[128:131], v[190:193], v[108:111]
	v_mfma_f32_16x16x32_bf16 v[104:107], v[136:139], v[190:193], v[104:107]
	v_mfma_f32_16x16x32_bf16 v[92:95], v[128:131], v[198:201], v[92:95]
	v_mfma_f32_16x16x32_bf16 v[88:91], v[136:139], v[198:201], v[88:91]
	v_mfma_f32_16x16x32_bf16 v[76:79], v[128:131], v[206:209], v[76:79]
	v_mfma_f32_16x16x32_bf16 v[72:75], v[136:139], v[206:209], v[72:75]
	v_mfma_f32_16x16x32_bf16 v[124:127], v[132:135], v[186:189], v[124:127]
	v_mfma_f32_16x16x32_bf16 v[120:123], v[140:143], v[186:189], v[120:123]
	v_mfma_f32_16x16x32_bf16 v[108:111], v[132:135], v[194:197], v[108:111]
	v_mfma_f32_16x16x32_bf16 v[104:107], v[140:143], v[194:197], v[104:107]
	v_mfma_f32_16x16x32_bf16 v[92:95], v[132:135], v[202:205], v[92:95]
	v_mfma_f32_16x16x32_bf16 v[88:91], v[140:143], v[202:205], v[88:91]
	v_mfma_f32_16x16x32_bf16 v[76:79], v[132:135], v[210:213], v[76:79]
	v_mfma_f32_16x16x32_bf16 v[72:75], v[140:143], v[210:213], v[72:75]
	s_setprio 0
	s_setprio 1
	v_mfma_f32_16x16x32_bf16 v[116:119], v[156:159], v[182:185], v[116:119]
	v_mfma_f32_16x16x32_bf16 v[112:115], v[170:173], v[182:185], v[112:115]
	v_mfma_f32_16x16x32_bf16 v[100:103], v[156:159], v[190:193], v[100:103]
	v_mfma_f32_16x16x32_bf16 v[96:99], v[170:173], v[190:193], v[96:99]
	v_mfma_f32_16x16x32_bf16 v[84:87], v[156:159], v[198:201], v[84:87]
	v_mfma_f32_16x16x32_bf16 v[80:83], v[170:173], v[198:201], v[80:83]
	v_mfma_f32_16x16x32_bf16 v[68:71], v[156:159], v[206:209], v[68:71]
	v_mfma_f32_16x16x32_bf16 v[64:67], v[170:173], v[206:209], v[64:67]
	v_mfma_f32_16x16x32_bf16 v[116:119], v[160:163], v[186:189], v[116:119]
	v_mfma_f32_16x16x32_bf16 v[112:115], v[174:177], v[186:189], v[112:115]
	v_mfma_f32_16x16x32_bf16 v[100:103], v[160:163], v[194:197], v[100:103]
	v_mfma_f32_16x16x32_bf16 v[96:99], v[174:177], v[194:197], v[96:99]
	v_mfma_f32_16x16x32_bf16 v[84:87], v[160:163], v[202:205], v[84:87]
	v_mfma_f32_16x16x32_bf16 v[80:83], v[174:177], v[202:205], v[80:83]
	v_mfma_f32_16x16x32_bf16 v[68:71], v[160:163], v[210:213], v[68:71]
	v_mfma_f32_16x16x32_bf16 v[64:67], v[174:177], v[210:213], v[64:67]
	s_setprio 0
	s_barrier
	s_add_i32 s40, s69, s48
	v_lshl_add_u64 v[178:179], v[178:179], 0, s[20:21]
	s_mov_b32 m0, s40
	ds_read_b128 v[182:185], v167 offset:49152
	ds_read_b128 v[186:189], v167 offset:50176
	ds_read_b128 v[190:193], v167 offset:51200
	ds_read_b128 v[194:197], v167 offset:52224
	ds_read_b128 v[198:201], v167 offset:53248
	ds_read_b128 v[202:205], v167 offset:54272
	ds_read_b128 v[206:209], v167 offset:55296
	ds_read_b128 v[210:213], v167 offset:56320
	global_load_lds_dwordx4 v[178:179], off
	s_add_i32 m0, s40, 0x2000
	s_add_u32 s38, s38, 0x40080
	v_lshl_add_u64 v[178:179], v[214:215], 0, s[20:21]
	s_addc_u32 s39, s39, 0
	s_add_i32 s40, s70, s48
	global_load_lds_dwordx4 v[178:179], off
	v_lshl_add_u64 v[178:179], s[38:39], 0, v[144:145]
	s_mov_b32 m0, s40
	s_nop 0
	global_load_lds_dwordx4 v[178:179], off
	v_lshl_add_u64 v[178:179], s[38:39], 0, v[146:147]
	s_add_i32 m0, s40, 0x2000
	s_nop 0
	global_load_lds_dwordx4 v[178:179], off
	v_lshl_add_u64 v[178:179], v[216:217], 0, s[20:21]
	s_mov_b32 m0, s56
	s_nop 0
	global_load_lds_dwordx4 v[178:179], off
	v_lshl_add_u64 v[178:179], v[218:219], 0, s[20:21]
	s_mov_b32 m0, s57
	s_nop 0
	global_load_lds_dwordx4 v[178:179], off
	s_waitcnt vmcnt(8)
	s_waitcnt lgkmcnt(0)
	s_barrier
	s_setprio 1
	s_waitcnt lgkmcnt(0)
	v_mfma_f32_16x16x32_bf16 v[60:63], v[128:131], v[182:185], v[60:63]
	v_mfma_f32_16x16x32_bf16 v[56:59], v[136:139], v[182:185], v[56:59]
	v_mfma_f32_16x16x32_bf16 v[44:47], v[128:131], v[190:193], v[44:47]
	v_mfma_f32_16x16x32_bf16 v[40:43], v[136:139], v[190:193], v[40:43]
	v_mfma_f32_16x16x32_bf16 v[28:31], v[128:131], v[198:201], v[28:31]
	v_mfma_f32_16x16x32_bf16 v[24:27], v[136:139], v[198:201], v[24:27]
	v_mfma_f32_16x16x32_bf16 v[12:15], v[128:131], v[206:209], v[12:15]
	v_mfma_f32_16x16x32_bf16 v[8:11], v[136:139], v[206:209], v[8:11]
	v_mfma_f32_16x16x32_bf16 v[60:63], v[132:135], v[186:189], v[60:63]
	v_mfma_f32_16x16x32_bf16 v[56:59], v[140:143], v[186:189], v[56:59]
	v_mfma_f32_16x16x32_bf16 v[44:47], v[132:135], v[194:197], v[44:47]
	v_mfma_f32_16x16x32_bf16 v[40:43], v[140:143], v[194:197], v[40:43]
	v_mfma_f32_16x16x32_bf16 v[28:31], v[132:135], v[202:205], v[28:31]
	v_mfma_f32_16x16x32_bf16 v[24:27], v[140:143], v[202:205], v[24:27]
	v_mfma_f32_16x16x32_bf16 v[12:15], v[132:135], v[210:213], v[12:15]
	v_mfma_f32_16x16x32_bf16 v[8:11], v[140:143], v[210:213], v[8:11]
	s_setprio 0
	s_setprio 1
	v_mfma_f32_16x16x32_bf16 v[52:55], v[156:159], v[182:185], v[52:55]
	v_mfma_f32_16x16x32_bf16 v[48:51], v[170:173], v[182:185], v[48:51]
	v_mfma_f32_16x16x32_bf16 v[36:39], v[156:159], v[190:193], v[36:39]
	v_mfma_f32_16x16x32_bf16 v[32:35], v[170:173], v[190:193], v[32:35]
	v_mfma_f32_16x16x32_bf16 v[20:23], v[156:159], v[198:201], v[20:23]
	v_mfma_f32_16x16x32_bf16 v[16:19], v[170:173], v[198:201], v[16:19]
	v_mfma_f32_16x16x32_bf16 v[4:7], v[156:159], v[206:209], v[4:7]
	v_mfma_f32_16x16x32_bf16 v[0:3], v[170:173], v[206:209], v[0:3]
	v_mfma_f32_16x16x32_bf16 v[52:55], v[160:163], v[186:189], v[52:55]
	v_mfma_f32_16x16x32_bf16 v[48:51], v[174:177], v[186:189], v[48:51]
	v_mfma_f32_16x16x32_bf16 v[36:39], v[160:163], v[194:197], v[36:39]
	v_mfma_f32_16x16x32_bf16 v[32:35], v[174:177], v[194:197], v[32:35]
	v_mfma_f32_16x16x32_bf16 v[20:23], v[160:163], v[202:205], v[20:23]
	v_mfma_f32_16x16x32_bf16 v[16:19], v[174:177], v[202:205], v[16:19]
	v_mfma_f32_16x16x32_bf16 v[4:7], v[160:163], v[210:213], v[4:7]
	v_mfma_f32_16x16x32_bf16 v[0:3], v[174:177], v[210:213], v[0:3]
	s_setprio 0
	s_barrier
	s_add_i32 s68, s68, 2
	s_add_u32 s36, s36, 0x100
	s_addc_u32 s37, s37, 0
	s_add_u32 s66, s66, 0x100
	s_addc_u32 s67, s67, 0
	s_cmp_gt_u32 s68, 13
	s_cbranch_scc0 .LBB0_1436
.Lqk_join_6:
	s_and_b64 vcc, exec, s[22:23]
	s_cbranch_vccz .LBB0_1439
	s_barrier

.LBB0_1517:
	s_add_u32 s56, s26, 0x100
	v_mov_b32_e32 v0, 0
	s_addc_u32 s57, s27, 0
	s_mov_b32 s58, -2
	s_waitcnt lgkmcnt(0)
	v_mov_b32_e32 v1, v0
	v_mov_b32_e32 v2, v0
	v_mov_b32_e32 v3, v0
	v_mov_b32_e32 v4, v0
	v_mov_b32_e32 v5, v0
	v_mov_b32_e32 v6, v0
	v_mov_b32_e32 v7, v0
	v_mov_b32_e32 v16, v0
	v_mov_b32_e32 v17, v0
	v_mov_b32_e32 v18, v0
	v_mov_b32_e32 v19, v0
	v_mov_b32_e32 v20, v0
	v_mov_b32_e32 v21, v0
	v_mov_b32_e32 v22, v0
	v_mov_b32_e32 v23, v0
	v_mov_b32_e32 v32, v0
	v_mov_b32_e32 v33, v0
	v_mov_b32_e32 v34, v0
	v_mov_b32_e32 v35, v0
	v_mov_b32_e32 v36, v0
	v_mov_b32_e32 v37, v0
	v_mov_b32_e32 v38, v0
	v_mov_b32_e32 v39, v0
	v_mov_b32_e32 v48, v0
	v_mov_b32_e32 v49, v0
	v_mov_b32_e32 v50, v0
	v_mov_b32_e32 v51, v0
	v_mov_b32_e32 v52, v0
	v_mov_b32_e32 v53, v0
	v_mov_b32_e32 v54, v0
	v_mov_b32_e32 v55, v0
	v_mov_b32_e32 v8, v0
	v_mov_b32_e32 v9, v0
	v_mov_b32_e32 v10, v0
	v_mov_b32_e32 v11, v0
	v_mov_b32_e32 v12, v0
	v_mov_b32_e32 v13, v0
	v_mov_b32_e32 v14, v0
	v_mov_b32_e32 v15, v0
	v_mov_b32_e32 v24, v0
	v_mov_b32_e32 v25, v0
	v_mov_b32_e32 v26, v0
	v_mov_b32_e32 v27, v0
	v_mov_b32_e32 v28, v0
	v_mov_b32_e32 v29, v0
	v_mov_b32_e32 v30, v0
	v_mov_b32_e32 v31, v0
	v_mov_b32_e32 v40, v0
	v_mov_b32_e32 v41, v0
	v_mov_b32_e32 v42, v0
	v_mov_b32_e32 v43, v0
	v_mov_b32_e32 v44, v0
	v_mov_b32_e32 v45, v0
	v_mov_b32_e32 v46, v0
	v_mov_b32_e32 v47, v0
	v_mov_b32_e32 v56, v0
	v_mov_b32_e32 v57, v0
	v_mov_b32_e32 v58, v0
	v_mov_b32_e32 v59, v0
	v_mov_b32_e32 v60, v0
	v_mov_b32_e32 v61, v0
	v_mov_b32_e32 v62, v0
	v_mov_b32_e32 v63, v0
	v_mov_b32_e32 v64, v0
	v_mov_b32_e32 v65, v0
	v_mov_b32_e32 v66, v0
	v_mov_b32_e32 v67, v0
	v_mov_b32_e32 v68, v0
	v_mov_b32_e32 v69, v0
	v_mov_b32_e32 v70, v0
	v_mov_b32_e32 v71, v0
	v_mov_b32_e32 v80, v0
	v_mov_b32_e32 v81, v0
	v_mov_b32_e32 v82, v0
	v_mov_b32_e32 v83, v0
	v_mov_b32_e32 v84, v0
	v_mov_b32_e32 v85, v0
	v_mov_b32_e32 v86, v0
	v_mov_b32_e32 v87, v0
	v_mov_b32_e32 v96, v0
	v_mov_b32_e32 v97, v0
	v_mov_b32_e32 v98, v0
	v_mov_b32_e32 v99, v0
	v_mov_b32_e32 v100, v0
	v_mov_b32_e32 v101, v0
	v_mov_b32_e32 v102, v0
	v_mov_b32_e32 v103, v0
	v_mov_b32_e32 v112, v0
	v_mov_b32_e32 v113, v0
	v_mov_b32_e32 v114, v0
	v_mov_b32_e32 v115, v0
	v_mov_b32_e32 v116, v0
	v_mov_b32_e32 v117, v0
	v_mov_b32_e32 v118, v0
	v_mov_b32_e32 v119, v0
	v_mov_b32_e32 v72, v0
	v_mov_b32_e32 v73, v0
	v_mov_b32_e32 v74, v0
	v_mov_b32_e32 v75, v0
	v_mov_b32_e32 v76, v0
	v_mov_b32_e32 v77, v0
	v_mov_b32_e32 v78, v0
	v_mov_b32_e32 v79, v0
	v_mov_b32_e32 v88, v0
	v_mov_b32_e32 v89, v0
	v_mov_b32_e32 v90, v0
	v_mov_b32_e32 v91, v0
	v_mov_b32_e32 v92, v0
	v_mov_b32_e32 v93, v0
	v_mov_b32_e32 v94, v0
	v_mov_b32_e32 v95, v0
	v_mov_b32_e32 v104, v0
	v_mov_b32_e32 v105, v0
	v_mov_b32_e32 v106, v0
	v_mov_b32_e32 v107, v0
	v_mov_b32_e32 v108, v0
	v_mov_b32_e32 v109, v0
	v_mov_b32_e32 v110, v0
	v_mov_b32_e32 v111, v0
	v_mov_b32_e32 v120, v0
	v_mov_b32_e32 v121, v0
	v_mov_b32_e32 v122, v0
	v_mov_b32_e32 v123, v0
	v_mov_b32_e32 v124, v0
	v_mov_b32_e32 v125, v0
	v_mov_b32_e32 v126, v0
	v_mov_b32_e32 v127, v0
	s_branch .Lqk_skip_8

.Lmm_8_7:
	s_setprio 0
	s_barrier
	s_add_i32 s58, s58, 2
	s_add_u32 s56, s56, 0x100
	s_addc_u32 s57, s57, 0
	s_cmp_gt_u32 s58, 41
	s_mov_b64 s[24:25], s[26:27]
	s_cbranch_scc0 .Lqk_8
	s_branch .Lqk_join_8

.LBB0_1518:
	ds_read_b128 v[140:143], v182
	ds_read_b128 v[144:147], v182 offset:1024
	ds_read_b128 v[148:151], v182 offset:2048
	ds_read_b128 v[152:155], v182 offset:3072
	ds_read_b128 v[156:159], v183
	ds_read_b128 v[160:163], v183 offset:1024
	ds_read_b128 v[164:167], v183 offset:2048
	ds_read_b128 v[168:171], v183 offset:3072
	s_add_u32 s26, s24, 0x100
	s_addc_u32 s27, s25, 0
	s_cmp_eq_u32 s58, 40
	s_cselect_b32 s31, s9, s27
	s_cselect_b32 s30, s8, s26
	s_cselect_b32 s29, s23, s57
	s_cselect_b32 s28, s22, s56
	v_lshl_add_u64 v[210:211], s[24:25], 0, v[132:133]
	s_add_i32 m0, s39, 0xc000
	ds_read_b128 v[172:175], v184
	ds_read_b128 v[176:179], v184 offset:1024
	ds_read_b128 v[186:189], v184 offset:2048
	ds_read_b128 v[190:193], v184 offset:3072
	ds_read_b128 v[194:197], v184 offset:4096
	ds_read_b128 v[198:201], v184 offset:5120
	ds_read_b128 v[202:205], v184 offset:6144
	ds_read_b128 v[206:209], v184 offset:7168
	global_load_lds_dwordx4 v[210:211], off
	v_lshl_add_u64 v[210:211], s[24:25], 0, v[134:135]
	s_add_i32 m0, s39, 0xe000
	s_nop 0
	global_load_lds_dwordx4 v[210:211], off
	s_waitcnt vmcnt(8)
	s_waitcnt lgkmcnt(0)
	s_barrier
	s_setprio 1
	s_waitcnt lgkmcnt(0)
	v_mfma_f32_16x16x32_bf16 v[124:127], v[140:143], v[172:175], v[124:127]
	v_mfma_f32_16x16x32_bf16 v[120:123], v[148:151], v[172:175], v[120:123]
	v_mfma_f32_16x16x32_bf16 v[108:111], v[140:143], v[186:189], v[108:111]
	v_mfma_f32_16x16x32_bf16 v[104:107], v[148:151], v[186:189], v[104:107]
	v_mfma_f32_16x16x32_bf16 v[92:95], v[140:143], v[194:197], v[92:95]
	v_mfma_f32_16x16x32_bf16 v[88:91], v[148:151], v[194:197], v[88:91]
	v_mfma_f32_16x16x32_bf16 v[76:79], v[140:143], v[202:205], v[76:79]
	v_mfma_f32_16x16x32_bf16 v[72:75], v[148:151], v[202:205], v[72:75]
	v_mfma_f32_16x16x32_bf16 v[124:127], v[144:147], v[176:179], v[124:127]
	v_mfma_f32_16x16x32_bf16 v[120:123], v[152:155], v[176:179], v[120:123]
	v_mfma_f32_16x16x32_bf16 v[108:111], v[144:147], v[190:193], v[108:111]
	v_mfma_f32_16x16x32_bf16 v[104:107], v[152:155], v[190:193], v[104:107]
	v_mfma_f32_16x16x32_bf16 v[92:95], v[144:147], v[198:201], v[92:95]
	v_mfma_f32_16x16x32_bf16 v[88:91], v[152:155], v[198:201], v[88:91]
	v_mfma_f32_16x16x32_bf16 v[76:79], v[144:147], v[206:209], v[76:79]
	v_mfma_f32_16x16x32_bf16 v[72:75], v[152:155], v[206:209], v[72:75]
	s_setprio 0
	s_setprio 1
	v_mfma_f32_16x16x32_bf16 v[116:119], v[156:159], v[172:175], v[116:119]
	v_mfma_f32_16x16x32_bf16 v[112:115], v[164:167], v[172:175], v[112:115]
	v_mfma_f32_16x16x32_bf16 v[100:103], v[156:159], v[186:189], v[100:103]
	v_mfma_f32_16x16x32_bf16 v[96:99], v[164:167], v[186:189], v[96:99]
	v_mfma_f32_16x16x32_bf16 v[84:87], v[156:159], v[194:197], v[84:87]
	v_mfma_f32_16x16x32_bf16 v[80:83], v[164:167], v[194:197], v[80:83]
	v_mfma_f32_16x16x32_bf16 v[68:71], v[156:159], v[202:205], v[68:71]
	v_mfma_f32_16x16x32_bf16 v[64:67], v[164:167], v[202:205], v[64:67]
	v_mfma_f32_16x16x32_bf16 v[116:119], v[160:163], v[176:179], v[116:119]
	v_mfma_f32_16x16x32_bf16 v[112:115], v[168:171], v[176:179], v[112:115]
	v_mfma_f32_16x16x32_bf16 v[100:103], v[160:163], v[190:193], v[100:103]
	v_mfma_f32_16x16x32_bf16 v[96:99], v[168:171], v[190:193], v[96:99]
	v_mfma_f32_16x16x32_bf16 v[84:87], v[160:163], v[198:201], v[84:87]
	v_mfma_f32_16x16x32_bf16 v[80:83], v[168:171], v[198:201], v[80:83]
	v_mfma_f32_16x16x32_bf16 v[68:71], v[160:163], v[206:209], v[68:71]
	v_mfma_f32_16x16x32_bf16 v[64:67], v[168:171], v[206:209], v[64:67]
	s_setprio 0
	s_barrier
	s_add_i32 s24, s50, s38
	v_lshl_add_u64 v[210:211], s[28:29], 0, v[128:129]
	s_mov_b32 m0, s24
	ds_read_b128 v[172:175], v184 offset:16384
	ds_read_b128 v[176:179], v184 offset:17408
	ds_read_b128 v[186:189], v184 offset:18432
	ds_read_b128 v[190:193], v184 offset:19456
	ds_read_b128 v[194:197], v184 offset:20480
	ds_read_b128 v[198:201], v184 offset:21504
	ds_read_b128 v[202:205], v184 offset:22528
	ds_read_b128 v[206:209], v184 offset:23552
	global_load_lds_dwordx4 v[210:211], off
	s_add_i32 m0, s24, 0x2000
	s_add_u32 s24, s28, 0xb0000
	v_lshl_add_u64 v[212:213], s[28:29], 0, v[130:131]
	s_addc_u32 s25, s29, 0
	s_add_i32 s59, s51, s38
	global_load_lds_dwordx4 v[212:213], off
	v_lshl_add_u64 v[214:215], s[24:25], 0, v[128:129]
	s_mov_b32 m0, s59
	v_lshl_add_u64 v[216:217], s[30:31], 0, v[130:131]
	global_load_lds_dwordx4 v[214:215], off
	v_lshl_add_u64 v[214:215], s[24:25], 0, v[130:131]
	s_add_i32 m0, s59, 0x2000
	s_nop 0
	global_load_lds_dwordx4 v[214:215], off
	v_lshl_add_u64 v[214:215], s[30:31], 0, v[128:129]
	s_mov_b32 m0, s39
	s_nop 0
	global_load_lds_dwordx4 v[214:215], off
	s_mov_b32 m0, s40
	s_nop 0
	global_load_lds_dwordx4 v[216:217], off
	s_waitcnt vmcnt(8)
	s_waitcnt lgkmcnt(0)
	s_barrier
	s_setprio 1
	s_waitcnt lgkmcnt(0)
	v_mfma_f32_16x16x32_bf16 v[60:63], v[140:143], v[172:175], v[60:63]
	v_mfma_f32_16x16x32_bf16 v[56:59], v[148:151], v[172:175], v[56:59]
	v_mfma_f32_16x16x32_bf16 v[44:47], v[140:143], v[186:189], v[44:47]
	v_mfma_f32_16x16x32_bf16 v[40:43], v[148:151], v[186:189], v[40:43]
	v_mfma_f32_16x16x32_bf16 v[28:31], v[140:143], v[194:197], v[28:31]
	v_mfma_f32_16x16x32_bf16 v[24:27], v[148:151], v[194:197], v[24:27]
	v_mfma_f32_16x16x32_bf16 v[12:15], v[140:143], v[202:205], v[12:15]
	v_mfma_f32_16x16x32_bf16 v[8:11], v[148:151], v[202:205], v[8:11]
	v_mfma_f32_16x16x32_bf16 v[60:63], v[144:147], v[176:179], v[60:63]
	v_mfma_f32_16x16x32_bf16 v[56:59], v[152:155], v[176:179], v[56:59]
	v_mfma_f32_16x16x32_bf16 v[44:47], v[144:147], v[190:193], v[44:47]
	v_mfma_f32_16x16x32_bf16 v[40:43], v[152:155], v[190:193], v[40:43]
	v_mfma_f32_16x16x32_bf16 v[28:31], v[144:147], v[198:201], v[28:31]
	v_mfma_f32_16x16x32_bf16 v[24:27], v[152:155], v[198:201], v[24:27]
	v_mfma_f32_16x16x32_bf16 v[12:15], v[144:147], v[206:209], v[12:15]
	v_mfma_f32_16x16x32_bf16 v[8:11], v[152:155], v[206:209], v[8:11]
	s_setprio 0
	s_setprio 1
	v_mfma_f32_16x16x32_bf16 v[52:55], v[156:159], v[172:175], v[52:55]
	v_mfma_f32_16x16x32_bf16 v[48:51], v[164:167], v[172:175], v[48:51]
	v_mfma_f32_16x16x32_bf16 v[36:39], v[156:159], v[186:189], v[36:39]
	v_mfma_f32_16x16x32_bf16 v[32:35], v[164:167], v[186:189], v[32:35]
	v_mfma_f32_16x16x32_bf16 v[20:23], v[156:159], v[194:197], v[20:23]
	v_mfma_f32_16x16x32_bf16 v[16:19], v[164:167], v[194:197], v[16:19]
	v_mfma_f32_16x16x32_bf16 v[4:7], v[156:159], v[202:205], v[4:7]
	v_mfma_f32_16x16x32_bf16 v[0:3], v[164:167], v[202:205], v[0:3]
	v_mfma_f32_16x16x32_bf16 v[52:55], v[160:163], v[176:179], v[52:55]
	v_mfma_f32_16x16x32_bf16 v[48:51], v[168:171], v[176:179], v[48:51]
	v_mfma_f32_16x16x32_bf16 v[36:39], v[160:163], v[190:193], v[36:39]
	v_mfma_f32_16x16x32_bf16 v[32:35], v[168:171], v[190:193], v[32:35]
	v_mfma_f32_16x16x32_bf16 v[20:23], v[160:163], v[198:201], v[20:23]
	v_mfma_f32_16x16x32_bf16 v[16:19], v[168:171], v[198:201], v[16:19]
	v_mfma_f32_16x16x32_bf16 v[4:7], v[160:163], v[206:209], v[4:7]
	v_mfma_f32_16x16x32_bf16 v[0:3], v[168:171], v[206:209], v[0:3]
	s_setprio 0
	s_barrier
	s_add_i32 s59, 0, 0x18000
	s_add_i32 s63, 0, 0x1c000
	v_add_u32_e32 v152, s59, v181
	v_add_u32_e32 v168, s63, v181
	ds_read_b128 v[140:143], v152
	ds_read_b128 v[144:147], v152 offset:1024
	ds_read_b128 v[148:151], v152 offset:2048
	ds_read_b128 v[152:155], v152 offset:3072
	ds_read_b128 v[156:159], v168
	ds_read_b128 v[160:163], v168 offset:1024
	ds_read_b128 v[164:167], v168 offset:2048
	ds_read_b128 v[168:171], v168 offset:3072
	s_add_u32 s24, s30, 0xb0000
	s_addc_u32 s25, s31, 0
	s_mov_b32 m0, s41
	v_lshl_add_u64 v[218:219], s[24:25], 0, v[128:129]
	ds_read_b128 v[172:175], v184 offset:32768
	ds_read_b128 v[176:179], v184 offset:33792
	ds_read_b128 v[186:189], v184 offset:34816
	ds_read_b128 v[190:193], v184 offset:35840
	ds_read_b128 v[194:197], v184 offset:36864
	ds_read_b128 v[198:201], v184 offset:37888
	ds_read_b128 v[202:205], v184 offset:38912
	ds_read_b128 v[206:209], v184 offset:39936
	global_load_lds_dwordx4 v[218:219], off
	v_lshl_add_u64 v[218:219], s[24:25], 0, v[130:131]
	s_mov_b32 m0, s42
	s_nop 0
	global_load_lds_dwordx4 v[218:219], off
	s_waitcnt vmcnt(8)
	s_waitcnt lgkmcnt(0)
	s_barrier
	s_setprio 1
	s_waitcnt lgkmcnt(0)
	v_mfma_f32_16x16x32_bf16 v[124:127], v[140:143], v[172:175], v[124:127]
	v_mfma_f32_16x16x32_bf16 v[120:123], v[148:151], v[172:175], v[120:123]
	v_mfma_f32_16x16x32_bf16 v[108:111], v[140:143], v[186:189], v[108:111]
	v_mfma_f32_16x16x32_bf16 v[104:107], v[148:151], v[186:189], v[104:107]
	v_mfma_f32_16x16x32_bf16 v[92:95], v[140:143], v[194:197], v[92:95]
	v_mfma_f32_16x16x32_bf16 v[88:91], v[148:151], v[194:197], v[88:91]
	v_mfma_f32_16x16x32_bf16 v[76:79], v[140:143], v[202:205], v[76:79]
	v_mfma_f32_16x16x32_bf16 v[72:75], v[148:151], v[202:205], v[72:75]
	v_mfma_f32_16x16x32_bf16 v[124:127], v[144:147], v[176:179], v[124:127]
	v_mfma_f32_16x16x32_bf16 v[120:123], v[152:155], v[176:179], v[120:123]
	v_mfma_f32_16x16x32_bf16 v[108:111], v[144:147], v[190:193], v[108:111]
	v_mfma_f32_16x16x32_bf16 v[104:107], v[152:155], v[190:193], v[104:107]
	v_mfma_f32_16x16x32_bf16 v[92:95], v[144:147], v[198:201], v[92:95]
	v_mfma_f32_16x16x32_bf16 v[88:91], v[152:155], v[198:201], v[88:91]
	v_mfma_f32_16x16x32_bf16 v[76:79], v[144:147], v[206:209], v[76:79]
	v_mfma_f32_16x16x32_bf16 v[72:75], v[152:155], v[206:209], v[72:75]
	s_setprio 0
	s_setprio 1
	v_mfma_f32_16x16x32_bf16 v[116:119], v[156:159], v[172:175], v[116:119]
	v_mfma_f32_16x16x32_bf16 v[112:115], v[164:167], v[172:175], v[112:115]
	v_mfma_f32_16x16x32_bf16 v[100:103], v[156:159], v[186:189], v[100:103]
	v_mfma_f32_16x16x32_bf16 v[96:99], v[164:167], v[186:189], v[96:99]
	v_mfma_f32_16x16x32_bf16 v[84:87], v[156:159], v[194:197], v[84:87]
	v_mfma_f32_16x16x32_bf16 v[80:83], v[164:167], v[194:197], v[80:83]
	v_mfma_f32_16x16x32_bf16 v[68:71], v[156:159], v[202:205], v[68:71]
	v_mfma_f32_16x16x32_bf16 v[64:67], v[164:167], v[202:205], v[64:67]
	v_mfma_f32_16x16x32_bf16 v[116:119], v[160:163], v[176:179], v[116:119]
	v_mfma_f32_16x16x32_bf16 v[112:115], v[168:171], v[176:179], v[112:115]
	v_mfma_f32_16x16x32_bf16 v[100:103], v[160:163], v[190:193], v[100:103]
	v_mfma_f32_16x16x32_bf16 v[96:99], v[168:171], v[190:193], v[96:99]
	v_mfma_f32_16x16x32_bf16 v[84:87], v[160:163], v[198:201], v[84:87]
	v_mfma_f32_16x16x32_bf16 v[80:83], v[168:171], v[198:201], v[80:83]
	v_mfma_f32_16x16x32_bf16 v[68:71], v[160:163], v[206:209], v[68:71]
	v_mfma_f32_16x16x32_bf16 v[64:67], v[168:171], v[206:209], v[64:67]
	s_setprio 0
	s_barrier
	s_add_i32 s24, s59, s38
	v_lshl_add_u64 v[210:211], v[210:211], 0, s[18:19]
	s_mov_b32 m0, s24
	ds_read_b128 v[172:175], v184 offset:49152
	ds_read_b128 v[176:179], v184 offset:50176
	ds_read_b128 v[186:189], v184 offset:51200
	ds_read_b128 v[190:193], v184 offset:52224
	ds_read_b128 v[194:197], v184 offset:53248
	ds_read_b128 v[198:201], v184 offset:54272
	ds_read_b128 v[202:205], v184 offset:55296
	ds_read_b128 v[206:209], v184 offset:56320
	global_load_lds_dwordx4 v[210:211], off
	s_add_i32 m0, s24, 0x2000
	s_add_u32 s24, s28, 0xb0080
	v_lshl_add_u64 v[210:211], v[212:213], 0, s[18:19]
	s_addc_u32 s25, s29, 0
	s_add_i32 s28, s63, s38
	global_load_lds_dwordx4 v[210:211], off
	v_lshl_add_u64 v[210:211], s[24:25], 0, v[128:129]
	s_mov_b32 m0, s28
	s_nop 0
	global_load_lds_dwordx4 v[210:211], off
	v_lshl_add_u64 v[210:211], s[24:25], 0, v[130:131]
	s_add_i32 m0, s28, 0x2000
	s_nop 0
	global_load_lds_dwordx4 v[210:211], off
	v_lshl_add_u64 v[210:211], v[214:215], 0, s[18:19]
	s_mov_b32 m0, s48
	s_nop 0
	global_load_lds_dwordx4 v[210:211], off
	v_lshl_add_u64 v[210:211], v[216:217], 0, s[18:19]
	s_mov_b32 m0, s49
	s_nop 0
	global_load_lds_dwordx4 v[210:211], off
	s_waitcnt vmcnt(8)
	s_waitcnt lgkmcnt(0)
	s_barrier
	s_setprio 1
	s_waitcnt lgkmcnt(0)
	v_mfma_f32_16x16x32_bf16 v[60:63], v[140:143], v[172:175], v[60:63]
	v_mfma_f32_16x16x32_bf16 v[56:59], v[148:151], v[172:175], v[56:59]
	v_mfma_f32_16x16x32_bf16 v[44:47], v[140:143], v[186:189], v[44:47]
	v_mfma_f32_16x16x32_bf16 v[40:43], v[148:151], v[186:189], v[40:43]
	v_mfma_f32_16x16x32_bf16 v[28:31], v[140:143], v[194:197], v[28:31]
	v_mfma_f32_16x16x32_bf16 v[24:27], v[148:151], v[194:197], v[24:27]
	v_mfma_f32_16x16x32_bf16 v[12:15], v[140:143], v[202:205], v[12:15]
	v_mfma_f32_16x16x32_bf16 v[8:11], v[148:151], v[202:205], v[8:11]
	v_mfma_f32_16x16x32_bf16 v[60:63], v[144:147], v[176:179], v[60:63]
	v_mfma_f32_16x16x32_bf16 v[56:59], v[152:155], v[176:179], v[56:59]
	v_mfma_f32_16x16x32_bf16 v[44:47], v[144:147], v[190:193], v[44:47]
	v_mfma_f32_16x16x32_bf16 v[40:43], v[152:155], v[190:193], v[40:43]
	v_mfma_f32_16x16x32_bf16 v[28:31], v[144:147], v[198:201], v[28:31]
	v_mfma_f32_16x16x32_bf16 v[24:27], v[152:155], v[198:201], v[24:27]
	v_mfma_f32_16x16x32_bf16 v[12:15], v[144:147], v[206:209], v[12:15]
	v_mfma_f32_16x16x32_bf16 v[8:11], v[152:155], v[206:209], v[8:11]
	s_setprio 0
	s_setprio 1
	v_mfma_f32_16x16x32_bf16 v[52:55], v[156:159], v[172:175], v[52:55]
	v_mfma_f32_16x16x32_bf16 v[48:51], v[164:167], v[172:175], v[48:51]
	v_mfma_f32_16x16x32_bf16 v[36:39], v[156:159], v[186:189], v[36:39]
	v_mfma_f32_16x16x32_bf16 v[32:35], v[164:167], v[186:189], v[32:35]
	v_mfma_f32_16x16x32_bf16 v[20:23], v[156:159], v[194:197], v[20:23]
	v_mfma_f32_16x16x32_bf16 v[16:19], v[164:167], v[194:197], v[16:19]
	v_mfma_f32_16x16x32_bf16 v[4:7], v[156:159], v[202:205], v[4:7]
	v_mfma_f32_16x16x32_bf16 v[0:3], v[164:167], v[202:205], v[0:3]
	v_mfma_f32_16x16x32_bf16 v[52:55], v[160:163], v[176:179], v[52:55]
	v_mfma_f32_16x16x32_bf16 v[48:51], v[168:171], v[176:179], v[48:51]
	v_mfma_f32_16x16x32_bf16 v[36:39], v[160:163], v[190:193], v[36:39]
	v_mfma_f32_16x16x32_bf16 v[32:35], v[168:171], v[190:193], v[32:35]
	v_mfma_f32_16x16x32_bf16 v[20:23], v[160:163], v[198:201], v[20:23]
	v_mfma_f32_16x16x32_bf16 v[16:19], v[168:171], v[198:201], v[16:19]
	v_mfma_f32_16x16x32_bf16 v[4:7], v[160:163], v[206:209], v[4:7]
	v_mfma_f32_16x16x32_bf16 v[0:3], v[168:171], v[206:209], v[0:3]
	s_setprio 0
	s_barrier
	s_add_i32 s58, s58, 2
	s_add_u32 s56, s56, 0x100
	s_addc_u32 s57, s57, 0
	s_cmp_gt_u32 s58, 41
	s_mov_b64 s[24:25], s[26:27]
	s_cbranch_scc0 .LBB0_1518
.Lqk_join_8:
	s_and_b64 vcc, exec, s[20:21]
	s_cbranch_vccz .LBB0_1521
	s_barrier

.LBB0_1834:
	s_ashr_i32 s23, s22, 31
	s_lshl_b64 s[24:25], s[22:23], 19
	s_add_u32 s24, s40, s24
	s_addc_u32 s25, s41, s25
	s_and_b64 s[26:27], s[6:7], exec
	s_cselect_b32 s23, s25, s35
	s_cselect_b32 s29, s24, s34
	s_ashr_i32 s21, s20, 31
	s_lshl_b64 s[26:27], s[20:21], 19
	s_add_u32 s26, s42, s26
	s_addc_u32 s27, s43, s27
	s_and_b64 s[38:39], s[6:7], exec
	s_cselect_b32 s21, s27, s37
	s_cselect_b32 s57, s26, s36
	s_add_u32 s34, s34, 0x40080
	s_addc_u32 s35, s35, 0
	s_add_u32 s58, s36, 0x100
	v_mov_b32_e32 v0, 0
	s_addc_u32 s59, s37, 0
	s_mov_b32 s63, -2
	s_waitcnt lgkmcnt(0)
	v_mov_b32_e32 v1, v0
	v_mov_b32_e32 v2, v0
	v_mov_b32_e32 v3, v0
	v_mov_b32_e32 v4, v0
	v_mov_b32_e32 v5, v0
	v_mov_b32_e32 v6, v0
	v_mov_b32_e32 v7, v0
	v_mov_b32_e32 v16, v0
	v_mov_b32_e32 v17, v0
	v_mov_b32_e32 v18, v0
	v_mov_b32_e32 v19, v0
	v_mov_b32_e32 v20, v0
	v_mov_b32_e32 v21, v0
	v_mov_b32_e32 v22, v0
	v_mov_b32_e32 v23, v0
	v_mov_b32_e32 v32, v0
	v_mov_b32_e32 v33, v0
	v_mov_b32_e32 v34, v0
	v_mov_b32_e32 v35, v0
	v_mov_b32_e32 v36, v0
	v_mov_b32_e32 v37, v0
	v_mov_b32_e32 v38, v0
	v_mov_b32_e32 v39, v0
	v_mov_b32_e32 v48, v0
	v_mov_b32_e32 v49, v0
	v_mov_b32_e32 v50, v0
	v_mov_b32_e32 v51, v0
	v_mov_b32_e32 v52, v0
	v_mov_b32_e32 v53, v0
	v_mov_b32_e32 v54, v0
	v_mov_b32_e32 v55, v0
	v_mov_b32_e32 v8, v0
	v_mov_b32_e32 v9, v0
	v_mov_b32_e32 v10, v0
	v_mov_b32_e32 v11, v0
	v_mov_b32_e32 v12, v0
	v_mov_b32_e32 v13, v0
	v_mov_b32_e32 v14, v0
	s_waitcnt vmcnt(0)
	v_mov_b32_e32 v15, v0
	v_mov_b32_e32 v24, v0
	v_mov_b32_e32 v25, v0
	v_mov_b32_e32 v26, v0
	v_mov_b32_e32 v27, v0
	v_mov_b32_e32 v28, v0
	v_mov_b32_e32 v29, v0
	v_mov_b32_e32 v30, v0
	v_mov_b32_e32 v31, v0
	v_mov_b32_e32 v40, v0
	v_mov_b32_e32 v41, v0
	v_mov_b32_e32 v42, v0
	v_mov_b32_e32 v43, v0
	v_mov_b32_e32 v44, v0
	v_mov_b32_e32 v45, v0
	v_mov_b32_e32 v46, v0
	v_mov_b32_e32 v47, v0
	v_mov_b32_e32 v56, v0
	v_mov_b32_e32 v57, v0
	v_mov_b32_e32 v58, v0
	v_mov_b32_e32 v59, v0
	v_mov_b32_e32 v60, v0
	v_mov_b32_e32 v61, v0
	v_mov_b32_e32 v62, v0
	v_mov_b32_e32 v63, v0
	v_mov_b32_e32 v64, v0
	v_mov_b32_e32 v65, v0
	v_mov_b32_e32 v66, v0
	v_mov_b32_e32 v67, v0
	v_mov_b32_e32 v68, v0
	v_mov_b32_e32 v69, v0
	v_mov_b32_e32 v70, v0
	v_mov_b32_e32 v71, v0
	v_mov_b32_e32 v80, v0
	v_mov_b32_e32 v81, v0
	v_mov_b32_e32 v82, v0
	v_mov_b32_e32 v83, v0
	v_mov_b32_e32 v84, v0
	v_mov_b32_e32 v85, v0
	v_mov_b32_e32 v86, v0
	v_mov_b32_e32 v87, v0
	v_mov_b32_e32 v96, v0
	v_mov_b32_e32 v97, v0
	v_mov_b32_e32 v98, v0
	v_mov_b32_e32 v99, v0
	v_mov_b32_e32 v100, v0
	v_mov_b32_e32 v101, v0
	v_mov_b32_e32 v102, v0
	v_mov_b32_e32 v103, v0
	v_mov_b32_e32 v112, v0
	v_mov_b32_e32 v113, v0
	v_mov_b32_e32 v114, v0
	v_mov_b32_e32 v115, v0
	v_mov_b32_e32 v116, v0
	v_mov_b32_e32 v117, v0
	v_mov_b32_e32 v118, v0
	v_mov_b32_e32 v119, v0
	v_mov_b32_e32 v72, v0
	v_mov_b32_e32 v73, v0
	v_mov_b32_e32 v74, v0
	v_mov_b32_e32 v75, v0
	v_mov_b32_e32 v76, v0
	v_mov_b32_e32 v77, v0
	v_mov_b32_e32 v78, v0
	v_mov_b32_e32 v79, v0
	v_mov_b32_e32 v88, v0
	v_mov_b32_e32 v89, v0
	v_mov_b32_e32 v90, v0
	v_mov_b32_e32 v91, v0
	v_mov_b32_e32 v92, v0
	v_mov_b32_e32 v93, v0
	v_mov_b32_e32 v94, v0
	v_mov_b32_e32 v95, v0
	v_mov_b32_e32 v104, v0
	v_mov_b32_e32 v105, v0
	v_mov_b32_e32 v106, v0
	v_mov_b32_e32 v107, v0
	v_mov_b32_e32 v108, v0
	v_mov_b32_e32 v109, v0
	v_mov_b32_e32 v110, v0
	v_mov_b32_e32 v111, v0
	v_mov_b32_e32 v120, v0
	v_mov_b32_e32 v121, v0
	v_mov_b32_e32 v122, v0
	v_mov_b32_e32 v123, v0
	v_mov_b32_e32 v124, v0
	v_mov_b32_e32 v125, v0
	v_mov_b32_e32 v126, v0
	v_mov_b32_e32 v127, v0
	s_branch .Lqk_skip_11

.Lmm_11_7:
	s_setprio 0
	s_barrier
	s_add_i32 s63, s63, 2
	s_add_u32 s34, s34, 0x100
	s_addc_u32 s35, s35, 0
	s_add_u32 s58, s58, 0x100
	s_addc_u32 s59, s59, 0
	s_cmp_gt_u32 s63, 13
	s_cbranch_scc0 .Lqk_11
	s_branch .Lqk_join_11

.LBB0_1835:
	ds_read_b128 v[140:143], v182
	ds_read_b128 v[144:147], v182 offset:1024
	ds_read_b128 v[148:151], v182 offset:2048
	ds_read_b128 v[152:155], v182 offset:3072
	ds_read_b128 v[156:159], v183
	ds_read_b128 v[160:163], v183 offset:1024
	ds_read_b128 v[164:167], v183 offset:2048
	ds_read_b128 v[168:171], v183 offset:3072
	s_add_u32 s36, s34, 0xfffc0080
	s_addc_u32 s37, s35, -1
	s_cmp_eq_u32 s63, 12
	s_cselect_b32 s39, s23, s37
	s_cselect_b32 s38, s29, s36
	s_cselect_b32 s37, s21, s59
	s_cselect_b32 s36, s57, s58
	v_lshl_add_u64 v[210:211], s[34:35], 0, v[132:133]
	s_add_i32 m0, s31, 0xc000
	ds_read_b128 v[172:175], v184
	ds_read_b128 v[176:179], v184 offset:1024
	ds_read_b128 v[186:189], v184 offset:2048
	ds_read_b128 v[190:193], v184 offset:3072
	ds_read_b128 v[194:197], v184 offset:4096
	ds_read_b128 v[198:201], v184 offset:5120
	ds_read_b128 v[202:205], v184 offset:6144
	ds_read_b128 v[206:209], v184 offset:7168
	global_load_lds_dwordx4 v[210:211], off
	v_lshl_add_u64 v[210:211], s[34:35], 0, v[134:135]
	s_add_i32 m0, s31, 0xe000
	s_nop 0
	global_load_lds_dwordx4 v[210:211], off
	s_waitcnt vmcnt(8)
	s_waitcnt lgkmcnt(0)
	s_barrier
	s_setprio 1
	s_waitcnt lgkmcnt(0)
	v_mfma_f32_16x16x32_bf16 v[124:127], v[140:143], v[172:175], v[124:127]
	v_mfma_f32_16x16x32_bf16 v[120:123], v[148:151], v[172:175], v[120:123]
	v_mfma_f32_16x16x32_bf16 v[108:111], v[140:143], v[186:189], v[108:111]
	v_mfma_f32_16x16x32_bf16 v[104:107], v[148:151], v[186:189], v[104:107]
	v_mfma_f32_16x16x32_bf16 v[92:95], v[140:143], v[194:197], v[92:95]
	v_mfma_f32_16x16x32_bf16 v[88:91], v[148:151], v[194:197], v[88:91]
	v_mfma_f32_16x16x32_bf16 v[76:79], v[140:143], v[202:205], v[76:79]
	v_mfma_f32_16x16x32_bf16 v[72:75], v[148:151], v[202:205], v[72:75]
	v_mfma_f32_16x16x32_bf16 v[124:127], v[144:147], v[176:179], v[124:127]
	v_mfma_f32_16x16x32_bf16 v[120:123], v[152:155], v[176:179], v[120:123]
	v_mfma_f32_16x16x32_bf16 v[108:111], v[144:147], v[190:193], v[108:111]
	v_mfma_f32_16x16x32_bf16 v[104:107], v[152:155], v[190:193], v[104:107]
	v_mfma_f32_16x16x32_bf16 v[92:95], v[144:147], v[198:201], v[92:95]
	v_mfma_f32_16x16x32_bf16 v[88:91], v[152:155], v[198:201], v[88:91]
	v_mfma_f32_16x16x32_bf16 v[76:79], v[144:147], v[206:209], v[76:79]
	v_mfma_f32_16x16x32_bf16 v[72:75], v[152:155], v[206:209], v[72:75]
	s_setprio 0
	s_setprio 1
	v_mfma_f32_16x16x32_bf16 v[116:119], v[156:159], v[172:175], v[116:119]
	v_mfma_f32_16x16x32_bf16 v[112:115], v[164:167], v[172:175], v[112:115]
	v_mfma_f32_16x16x32_bf16 v[100:103], v[156:159], v[186:189], v[100:103]
	v_mfma_f32_16x16x32_bf16 v[96:99], v[164:167], v[186:189], v[96:99]
	v_mfma_f32_16x16x32_bf16 v[84:87], v[156:159], v[194:197], v[84:87]
	v_mfma_f32_16x16x32_bf16 v[80:83], v[164:167], v[194:197], v[80:83]
	v_mfma_f32_16x16x32_bf16 v[68:71], v[156:159], v[202:205], v[68:71]
	v_mfma_f32_16x16x32_bf16 v[64:67], v[164:167], v[202:205], v[64:67]
	v_mfma_f32_16x16x32_bf16 v[116:119], v[160:163], v[176:179], v[116:119]
	v_mfma_f32_16x16x32_bf16 v[112:115], v[168:171], v[176:179], v[112:115]
	v_mfma_f32_16x16x32_bf16 v[100:103], v[160:163], v[190:193], v[100:103]
	v_mfma_f32_16x16x32_bf16 v[96:99], v[168:171], v[190:193], v[96:99]
	v_mfma_f32_16x16x32_bf16 v[84:87], v[160:163], v[198:201], v[84:87]
	v_mfma_f32_16x16x32_bf16 v[80:83], v[168:171], v[198:201], v[80:83]
	v_mfma_f32_16x16x32_bf16 v[68:71], v[160:163], v[206:209], v[68:71]
	v_mfma_f32_16x16x32_bf16 v[64:67], v[168:171], v[206:209], v[64:67]
	s_setprio 0
	s_barrier
	s_add_i32 s64, s55, s44
	v_lshl_add_u64 v[210:211], s[36:37], 0, v[128:129]
	s_mov_b32 m0, s64
	ds_read_b128 v[172:175], v184 offset:16384
	ds_read_b128 v[176:179], v184 offset:17408
	ds_read_b128 v[186:189], v184 offset:18432
	ds_read_b128 v[190:193], v184 offset:19456
	ds_read_b128 v[194:197], v184 offset:20480
	ds_read_b128 v[198:201], v184 offset:21504
	ds_read_b128 v[202:205], v184 offset:22528
	ds_read_b128 v[206:209], v184 offset:23552
	global_load_lds_dwordx4 v[210:211], off
	s_add_i32 m0, s64, 0x2000
	s_add_u32 s64, s36, 0x40000
	v_lshl_add_u64 v[212:213], s[36:37], 0, v[130:131]
	s_addc_u32 s65, s37, 0
	s_add_i32 s66, s56, s44
	global_load_lds_dwordx4 v[212:213], off
	v_lshl_add_u64 v[214:215], s[64:65], 0, v[128:129]
	s_mov_b32 m0, s66
	v_lshl_add_u64 v[216:217], s[38:39], 0, v[130:131]
	global_load_lds_dwordx4 v[214:215], off
	v_lshl_add_u64 v[214:215], s[64:65], 0, v[130:131]
	s_add_i32 m0, s66, 0x2000
	s_nop 0
	global_load_lds_dwordx4 v[214:215], off
	v_lshl_add_u64 v[214:215], s[38:39], 0, v[128:129]
	s_mov_b32 m0, s31
	s_nop 0
	global_load_lds_dwordx4 v[214:215], off
	s_mov_b32 m0, s45
	s_nop 0
	global_load_lds_dwordx4 v[216:217], off
	s_waitcnt vmcnt(8)
	s_waitcnt lgkmcnt(0)
	s_barrier
	s_setprio 1
	s_waitcnt lgkmcnt(0)
	v_mfma_f32_16x16x32_bf16 v[60:63], v[140:143], v[172:175], v[60:63]
	v_mfma_f32_16x16x32_bf16 v[56:59], v[148:151], v[172:175], v[56:59]
	v_mfma_f32_16x16x32_bf16 v[44:47], v[140:143], v[186:189], v[44:47]
	v_mfma_f32_16x16x32_bf16 v[40:43], v[148:151], v[186:189], v[40:43]
	v_mfma_f32_16x16x32_bf16 v[28:31], v[140:143], v[194:197], v[28:31]
	v_mfma_f32_16x16x32_bf16 v[24:27], v[148:151], v[194:197], v[24:27]
	v_mfma_f32_16x16x32_bf16 v[12:15], v[140:143], v[202:205], v[12:15]
	v_mfma_f32_16x16x32_bf16 v[8:11], v[148:151], v[202:205], v[8:11]
	v_mfma_f32_16x16x32_bf16 v[60:63], v[144:147], v[176:179], v[60:63]
	v_mfma_f32_16x16x32_bf16 v[56:59], v[152:155], v[176:179], v[56:59]
	v_mfma_f32_16x16x32_bf16 v[44:47], v[144:147], v[190:193], v[44:47]
	v_mfma_f32_16x16x32_bf16 v[40:43], v[152:155], v[190:193], v[40:43]
	v_mfma_f32_16x16x32_bf16 v[28:31], v[144:147], v[198:201], v[28:31]
	v_mfma_f32_16x16x32_bf16 v[24:27], v[152:155], v[198:201], v[24:27]
	v_mfma_f32_16x16x32_bf16 v[12:15], v[144:147], v[206:209], v[12:15]
	v_mfma_f32_16x16x32_bf16 v[8:11], v[152:155], v[206:209], v[8:11]
	s_setprio 0
	s_setprio 1
	v_mfma_f32_16x16x32_bf16 v[52:55], v[156:159], v[172:175], v[52:55]
	v_mfma_f32_16x16x32_bf16 v[48:51], v[164:167], v[172:175], v[48:51]
	v_mfma_f32_16x16x32_bf16 v[36:39], v[156:159], v[186:189], v[36:39]
	v_mfma_f32_16x16x32_bf16 v[32:35], v[164:167], v[186:189], v[32:35]
	v_mfma_f32_16x16x32_bf16 v[20:23], v[156:159], v[194:197], v[20:23]
	v_mfma_f32_16x16x32_bf16 v[16:19], v[164:167], v[194:197], v[16:19]
	v_mfma_f32_16x16x32_bf16 v[4:7], v[156:159], v[202:205], v[4:7]
	v_mfma_f32_16x16x32_bf16 v[0:3], v[164:167], v[202:205], v[0:3]
	v_mfma_f32_16x16x32_bf16 v[52:55], v[160:163], v[176:179], v[52:55]
	v_mfma_f32_16x16x32_bf16 v[48:51], v[168:171], v[176:179], v[48:51]
	v_mfma_f32_16x16x32_bf16 v[36:39], v[160:163], v[190:193], v[36:39]
	v_mfma_f32_16x16x32_bf16 v[32:35], v[168:171], v[190:193], v[32:35]
	v_mfma_f32_16x16x32_bf16 v[20:23], v[160:163], v[198:201], v[20:23]
	v_mfma_f32_16x16x32_bf16 v[16:19], v[168:171], v[198:201], v[16:19]
	v_mfma_f32_16x16x32_bf16 v[4:7], v[160:163], v[206:209], v[4:7]
	v_mfma_f32_16x16x32_bf16 v[0:3], v[168:171], v[206:209], v[0:3]
	s_setprio 0
	s_barrier
	s_add_i32 s64, 0, 0x18000
	s_add_i32 s65, 0, 0x1c000
	v_add_u32_e32 v152, s64, v181
	v_add_u32_e32 v168, s65, v181
	ds_read_b128 v[140:143], v152
	ds_read_b128 v[144:147], v152 offset:1024
	ds_read_b128 v[148:151], v152 offset:2048
	ds_read_b128 v[152:155], v152 offset:3072
	ds_read_b128 v[156:159], v168
	ds_read_b128 v[160:163], v168 offset:1024
	ds_read_b128 v[164:167], v168 offset:2048
	ds_read_b128 v[168:171], v168 offset:3072
	s_add_u32 s38, s38, 0x40000
	s_addc_u32 s39, s39, 0
	s_mov_b32 m0, s48
	v_lshl_add_u64 v[218:219], s[38:39], 0, v[128:129]
	ds_read_b128 v[172:175], v184 offset:32768
	ds_read_b128 v[176:179], v184 offset:33792
	ds_read_b128 v[186:189], v184 offset:34816
	ds_read_b128 v[190:193], v184 offset:35840
	ds_read_b128 v[194:197], v184 offset:36864
	ds_read_b128 v[198:201], v184 offset:37888
	ds_read_b128 v[202:205], v184 offset:38912
	ds_read_b128 v[206:209], v184 offset:39936
	global_load_lds_dwordx4 v[218:219], off
	v_lshl_add_u64 v[218:219], s[38:39], 0, v[130:131]
	s_mov_b32 m0, s49
	s_nop 0
	global_load_lds_dwordx4 v[218:219], off
	s_waitcnt vmcnt(8)
	s_waitcnt lgkmcnt(0)
	s_barrier
	s_setprio 1
	s_waitcnt lgkmcnt(0)
	v_mfma_f32_16x16x32_bf16 v[124:127], v[140:143], v[172:175], v[124:127]
	v_mfma_f32_16x16x32_bf16 v[120:123], v[148:151], v[172:175], v[120:123]
	v_mfma_f32_16x16x32_bf16 v[108:111], v[140:143], v[186:189], v[108:111]
	v_mfma_f32_16x16x32_bf16 v[104:107], v[148:151], v[186:189], v[104:107]
	v_mfma_f32_16x16x32_bf16 v[92:95], v[140:143], v[194:197], v[92:95]
	v_mfma_f32_16x16x32_bf16 v[88:91], v[148:151], v[194:197], v[88:91]
	v_mfma_f32_16x16x32_bf16 v[76:79], v[140:143], v[202:205], v[76:79]
	v_mfma_f32_16x16x32_bf16 v[72:75], v[148:151], v[202:205], v[72:75]
	v_mfma_f32_16x16x32_bf16 v[124:127], v[144:147], v[176:179], v[124:127]
	v_mfma_f32_16x16x32_bf16 v[120:123], v[152:155], v[176:179], v[120:123]
	v_mfma_f32_16x16x32_bf16 v[108:111], v[144:147], v[190:193], v[108:111]
	v_mfma_f32_16x16x32_bf16 v[104:107], v[152:155], v[190:193], v[104:107]
	v_mfma_f32_16x16x32_bf16 v[92:95], v[144:147], v[198:201], v[92:95]
	v_mfma_f32_16x16x32_bf16 v[88:91], v[152:155], v[198:201], v[88:91]
	v_mfma_f32_16x16x32_bf16 v[76:79], v[144:147], v[206:209], v[76:79]
	v_mfma_f32_16x16x32_bf16 v[72:75], v[152:155], v[206:209], v[72:75]
	s_setprio 0
	s_setprio 1
	v_mfma_f32_16x16x32_bf16 v[116:119], v[156:159], v[172:175], v[116:119]
	v_mfma_f32_16x16x32_bf16 v[112:115], v[164:167], v[172:175], v[112:115]
	v_mfma_f32_16x16x32_bf16 v[100:103], v[156:159], v[186:189], v[100:103]
	v_mfma_f32_16x16x32_bf16 v[96:99], v[164:167], v[186:189], v[96:99]
	v_mfma_f32_16x16x32_bf16 v[84:87], v[156:159], v[194:197], v[84:87]
	v_mfma_f32_16x16x32_bf16 v[80:83], v[164:167], v[194:197], v[80:83]
	v_mfma_f32_16x16x32_bf16 v[68:71], v[156:159], v[202:205], v[68:71]
	v_mfma_f32_16x16x32_bf16 v[64:67], v[164:167], v[202:205], v[64:67]
	v_mfma_f32_16x16x32_bf16 v[116:119], v[160:163], v[176:179], v[116:119]
	v_mfma_f32_16x16x32_bf16 v[112:115], v[168:171], v[176:179], v[112:115]
	v_mfma_f32_16x16x32_bf16 v[100:103], v[160:163], v[190:193], v[100:103]
	v_mfma_f32_16x16x32_bf16 v[96:99], v[168:171], v[190:193], v[96:99]
	v_mfma_f32_16x16x32_bf16 v[84:87], v[160:163], v[198:201], v[84:87]
	v_mfma_f32_16x16x32_bf16 v[80:83], v[168:171], v[198:201], v[80:83]
	v_mfma_f32_16x16x32_bf16 v[68:71], v[160:163], v[206:209], v[68:71]
	v_mfma_f32_16x16x32_bf16 v[64:67], v[168:171], v[206:209], v[64:67]
	s_setprio 0
	s_barrier
	s_add_i32 s38, s64, s44
	v_lshl_add_u64 v[210:211], v[210:211], 0, s[14:15]
	s_mov_b32 m0, s38
	ds_read_b128 v[172:175], v184 offset:49152
	ds_read_b128 v[176:179], v184 offset:50176
	ds_read_b128 v[186:189], v184 offset:51200
	ds_read_b128 v[190:193], v184 offset:52224
	ds_read_b128 v[194:197], v184 offset:53248
	ds_read_b128 v[198:201], v184 offset:54272
	ds_read_b128 v[202:205], v184 offset:55296
	ds_read_b128 v[206:209], v184 offset:56320
	global_load_lds_dwordx4 v[210:211], off
	s_add_i32 m0, s38, 0x2000
	s_add_u32 s36, s36, 0x40080
	v_lshl_add_u64 v[210:211], v[212:213], 0, s[14:15]
	s_addc_u32 s37, s37, 0
	s_add_i32 s38, s65, s44
	global_load_lds_dwordx4 v[210:211], off
	v_lshl_add_u64 v[210:211], s[36:37], 0, v[128:129]
	s_mov_b32 m0, s38
	s_nop 0
	global_load_lds_dwordx4 v[210:211], off
	v_lshl_add_u64 v[210:211], s[36:37], 0, v[130:131]
	s_add_i32 m0, s38, 0x2000
	s_nop 0
	global_load_lds_dwordx4 v[210:211], off
	v_lshl_add_u64 v[210:211], v[214:215], 0, s[14:15]
	s_mov_b32 m0, s53
	s_nop 0
	global_load_lds_dwordx4 v[210:211], off
	v_lshl_add_u64 v[210:211], v[216:217], 0, s[14:15]
	s_mov_b32 m0, s54
	s_nop 0
	global_load_lds_dwordx4 v[210:211], off
	s_waitcnt vmcnt(8)
	s_waitcnt lgkmcnt(0)
	s_barrier
	s_setprio 1
	s_waitcnt lgkmcnt(0)
	v_mfma_f32_16x16x32_bf16 v[60:63], v[140:143], v[172:175], v[60:63]
	v_mfma_f32_16x16x32_bf16 v[56:59], v[148:151], v[172:175], v[56:59]
	v_mfma_f32_16x16x32_bf16 v[44:47], v[140:143], v[186:189], v[44:47]
	v_mfma_f32_16x16x32_bf16 v[40:43], v[148:151], v[186:189], v[40:43]
	v_mfma_f32_16x16x32_bf16 v[28:31], v[140:143], v[194:197], v[28:31]
	v_mfma_f32_16x16x32_bf16 v[24:27], v[148:151], v[194:197], v[24:27]
	v_mfma_f32_16x16x32_bf16 v[12:15], v[140:143], v[202:205], v[12:15]
	v_mfma_f32_16x16x32_bf16 v[8:11], v[148:151], v[202:205], v[8:11]
	v_mfma_f32_16x16x32_bf16 v[60:63], v[144:147], v[176:179], v[60:63]
	v_mfma_f32_16x16x32_bf16 v[56:59], v[152:155], v[176:179], v[56:59]
	v_mfma_f32_16x16x32_bf16 v[44:47], v[144:147], v[190:193], v[44:47]
	v_mfma_f32_16x16x32_bf16 v[40:43], v[152:155], v[190:193], v[40:43]
	v_mfma_f32_16x16x32_bf16 v[28:31], v[144:147], v[198:201], v[28:31]
	v_mfma_f32_16x16x32_bf16 v[24:27], v[152:155], v[198:201], v[24:27]
	v_mfma_f32_16x16x32_bf16 v[12:15], v[144:147], v[206:209], v[12:15]
	v_mfma_f32_16x16x32_bf16 v[8:11], v[152:155], v[206:209], v[8:11]
	s_setprio 0
	s_setprio 1
	v_mfma_f32_16x16x32_bf16 v[52:55], v[156:159], v[172:175], v[52:55]
	v_mfma_f32_16x16x32_bf16 v[48:51], v[164:167], v[172:175], v[48:51]
	v_mfma_f32_16x16x32_bf16 v[36:39], v[156:159], v[186:189], v[36:39]
	v_mfma_f32_16x16x32_bf16 v[32:35], v[164:167], v[186:189], v[32:35]
	v_mfma_f32_16x16x32_bf16 v[20:23], v[156:159], v[194:197], v[20:23]
	v_mfma_f32_16x16x32_bf16 v[16:19], v[164:167], v[194:197], v[16:19]
	v_mfma_f32_16x16x32_bf16 v[4:7], v[156:159], v[202:205], v[4:7]
	v_mfma_f32_16x16x32_bf16 v[0:3], v[164:167], v[202:205], v[0:3]
	v_mfma_f32_16x16x32_bf16 v[52:55], v[160:163], v[176:179], v[52:55]
	v_mfma_f32_16x16x32_bf16 v[48:51], v[168:171], v[176:179], v[48:51]
	v_mfma_f32_16x16x32_bf16 v[36:39], v[160:163], v[190:193], v[36:39]
	v_mfma_f32_16x16x32_bf16 v[32:35], v[168:171], v[190:193], v[32:35]
	v_mfma_f32_16x16x32_bf16 v[20:23], v[160:163], v[198:201], v[20:23]
	v_mfma_f32_16x16x32_bf16 v[16:19], v[168:171], v[198:201], v[16:19]
	v_mfma_f32_16x16x32_bf16 v[4:7], v[160:163], v[206:209], v[4:7]
	v_mfma_f32_16x16x32_bf16 v[0:3], v[168:171], v[206:209], v[0:3]
	s_setprio 0
	s_barrier
	s_add_i32 s63, s63, 2
	s_add_u32 s34, s34, 0x100
	s_addc_u32 s35, s35, 0
	s_add_u32 s58, s58, 0x100
	s_addc_u32 s59, s59, 0
	s_cmp_gt_u32 s63, 13
	s_cbranch_scc0 .LBB0_1835
.Lqk_join_11:
	s_and_b64 vcc, exec, s[18:19]
	s_cbranch_vccz .LBB0_1838
	s_barrier

.LBB0_1916:
	s_add_u32 s49, s20, 0x100
	v_mov_b32_e32 v0, 0
	s_addc_u32 s50, s21, 0
	s_mov_b32 s51, -2
	s_waitcnt lgkmcnt(0)
	v_mov_b32_e32 v1, v0
	v_mov_b32_e32 v2, v0
	v_mov_b32_e32 v3, v0
	v_mov_b32_e32 v4, v0
	v_mov_b32_e32 v5, v0
	v_mov_b32_e32 v6, v0
	v_mov_b32_e32 v7, v0
	v_mov_b32_e32 v16, v0
	v_mov_b32_e32 v17, v0
	v_mov_b32_e32 v18, v0
	v_mov_b32_e32 v19, v0
	v_mov_b32_e32 v20, v0
	v_mov_b32_e32 v21, v0
	v_mov_b32_e32 v22, v0
	v_mov_b32_e32 v23, v0
	v_mov_b32_e32 v32, v0
	v_mov_b32_e32 v33, v0
	v_mov_b32_e32 v34, v0
	v_mov_b32_e32 v35, v0
	v_mov_b32_e32 v36, v0
	v_mov_b32_e32 v37, v0
	v_mov_b32_e32 v38, v0
	v_mov_b32_e32 v39, v0
	v_mov_b32_e32 v48, v0
	v_mov_b32_e32 v49, v0
	v_mov_b32_e32 v50, v0
	v_mov_b32_e32 v51, v0
	v_mov_b32_e32 v52, v0
	v_mov_b32_e32 v53, v0
	v_mov_b32_e32 v54, v0
	v_mov_b32_e32 v55, v0
	v_mov_b32_e32 v8, v0
	v_mov_b32_e32 v9, v0
	v_mov_b32_e32 v10, v0
	v_mov_b32_e32 v11, v0
	v_mov_b32_e32 v12, v0
	v_mov_b32_e32 v13, v0
	v_mov_b32_e32 v14, v0
	v_mov_b32_e32 v15, v0
	v_mov_b32_e32 v24, v0
	v_mov_b32_e32 v25, v0
	v_mov_b32_e32 v26, v0
	v_mov_b32_e32 v27, v0
	v_mov_b32_e32 v28, v0
	v_mov_b32_e32 v29, v0
	v_mov_b32_e32 v30, v0
	v_mov_b32_e32 v31, v0
	v_mov_b32_e32 v40, v0
	v_mov_b32_e32 v41, v0
	v_mov_b32_e32 v42, v0
	v_mov_b32_e32 v43, v0
	v_mov_b32_e32 v44, v0
	v_mov_b32_e32 v45, v0
	v_mov_b32_e32 v46, v0
	v_mov_b32_e32 v47, v0
	v_mov_b32_e32 v56, v0
	v_mov_b32_e32 v57, v0
	v_mov_b32_e32 v58, v0
	v_mov_b32_e32 v59, v0
	v_mov_b32_e32 v60, v0
	v_mov_b32_e32 v61, v0
	v_mov_b32_e32 v62, v0
	v_mov_b32_e32 v63, v0
	v_mov_b32_e32 v64, v0
	v_mov_b32_e32 v65, v0
	v_mov_b32_e32 v66, v0
	v_mov_b32_e32 v67, v0
	v_mov_b32_e32 v68, v0
	v_mov_b32_e32 v69, v0
	v_mov_b32_e32 v70, v0
	v_mov_b32_e32 v71, v0
	v_mov_b32_e32 v80, v0
	v_mov_b32_e32 v81, v0
	v_mov_b32_e32 v82, v0
	v_mov_b32_e32 v83, v0
	v_mov_b32_e32 v84, v0
	v_mov_b32_e32 v85, v0
	v_mov_b32_e32 v86, v0
	v_mov_b32_e32 v87, v0
	v_mov_b32_e32 v96, v0
	v_mov_b32_e32 v97, v0
	v_mov_b32_e32 v98, v0
	v_mov_b32_e32 v99, v0
	v_mov_b32_e32 v100, v0
	v_mov_b32_e32 v101, v0
	v_mov_b32_e32 v102, v0
	v_mov_b32_e32 v103, v0
	v_mov_b32_e32 v112, v0
	v_mov_b32_e32 v113, v0
	v_mov_b32_e32 v114, v0
	v_mov_b32_e32 v115, v0
	v_mov_b32_e32 v116, v0
	v_mov_b32_e32 v117, v0
	v_mov_b32_e32 v118, v0
	v_mov_b32_e32 v119, v0
	v_mov_b32_e32 v72, v0
	v_mov_b32_e32 v73, v0
	v_mov_b32_e32 v74, v0
	v_mov_b32_e32 v75, v0
	v_mov_b32_e32 v76, v0
	v_mov_b32_e32 v77, v0
	v_mov_b32_e32 v78, v0
	v_mov_b32_e32 v79, v0
	v_mov_b32_e32 v88, v0
	v_mov_b32_e32 v89, v0
	v_mov_b32_e32 v90, v0
	v_mov_b32_e32 v91, v0
	v_mov_b32_e32 v92, v0
	v_mov_b32_e32 v93, v0
	v_mov_b32_e32 v94, v0
	v_mov_b32_e32 v95, v0
	v_mov_b32_e32 v104, v0
	v_mov_b32_e32 v105, v0
	v_mov_b32_e32 v106, v0
	v_mov_b32_e32 v107, v0
	v_mov_b32_e32 v108, v0
	v_mov_b32_e32 v109, v0
	v_mov_b32_e32 v110, v0
	v_mov_b32_e32 v111, v0
	v_mov_b32_e32 v120, v0
	v_mov_b32_e32 v121, v0
	v_mov_b32_e32 v122, v0
	v_mov_b32_e32 v123, v0
	v_mov_b32_e32 v124, v0
	v_mov_b32_e32 v125, v0
	v_mov_b32_e32 v126, v0
	v_mov_b32_e32 v127, v0
	s_branch .Lqk_skip_13

.Lmm_13_7:
	s_setprio 0
	s_barrier
	s_add_i32 s51, s51, 2
	s_add_u32 s49, s49, 0x100
	s_addc_u32 s50, s50, 0
	s_cmp_gt_u32 s51, 41
	s_mov_b64 s[18:19], s[20:21]
	s_cbranch_scc0 .Lqk_13
	s_branch .Lqk_join_13

.LBB0_1917:
	ds_read_b128 v[140:143], v182
	ds_read_b128 v[144:147], v182 offset:1024
	ds_read_b128 v[148:151], v182 offset:2048
	ds_read_b128 v[152:155], v182 offset:3072
	ds_read_b128 v[156:159], v183
	ds_read_b128 v[160:163], v183 offset:1024
	ds_read_b128 v[164:167], v183 offset:2048
	ds_read_b128 v[168:171], v183 offset:3072
	s_add_u32 s20, s18, 0x100
	s_addc_u32 s21, s19, 0
	s_cmp_eq_u32 s51, 40
	s_cselect_b32 s25, s7, s21
	s_cselect_b32 s24, s6, s20
	s_cselect_b32 s23, s17, s50
	s_cselect_b32 s22, s16, s49
	v_lshl_add_u64 v[210:211], s[18:19], 0, v[132:133]
	s_add_i32 m0, s31, 0xc000
	ds_read_b128 v[172:175], v184
	ds_read_b128 v[176:179], v184 offset:1024
	ds_read_b128 v[186:189], v184 offset:2048
	ds_read_b128 v[190:193], v184 offset:3072
	ds_read_b128 v[194:197], v184 offset:4096
	ds_read_b128 v[198:201], v184 offset:5120
	ds_read_b128 v[202:205], v184 offset:6144
	ds_read_b128 v[206:209], v184 offset:7168
	global_load_lds_dwordx4 v[210:211], off
	v_lshl_add_u64 v[210:211], s[18:19], 0, v[134:135]
	s_add_i32 m0, s31, 0xe000
	s_nop 0
	global_load_lds_dwordx4 v[210:211], off
	s_waitcnt vmcnt(8)
	s_waitcnt lgkmcnt(0)
	s_barrier
	s_setprio 1
	s_waitcnt lgkmcnt(0)
	v_mfma_f32_16x16x32_bf16 v[124:127], v[140:143], v[172:175], v[124:127]
	v_mfma_f32_16x16x32_bf16 v[120:123], v[148:151], v[172:175], v[120:123]
	v_mfma_f32_16x16x32_bf16 v[108:111], v[140:143], v[186:189], v[108:111]
	v_mfma_f32_16x16x32_bf16 v[104:107], v[148:151], v[186:189], v[104:107]
	v_mfma_f32_16x16x32_bf16 v[92:95], v[140:143], v[194:197], v[92:95]
	v_mfma_f32_16x16x32_bf16 v[88:91], v[148:151], v[194:197], v[88:91]
	v_mfma_f32_16x16x32_bf16 v[76:79], v[140:143], v[202:205], v[76:79]
	v_mfma_f32_16x16x32_bf16 v[72:75], v[148:151], v[202:205], v[72:75]
	v_mfma_f32_16x16x32_bf16 v[124:127], v[144:147], v[176:179], v[124:127]
	v_mfma_f32_16x16x32_bf16 v[120:123], v[152:155], v[176:179], v[120:123]
	v_mfma_f32_16x16x32_bf16 v[108:111], v[144:147], v[190:193], v[108:111]
	v_mfma_f32_16x16x32_bf16 v[104:107], v[152:155], v[190:193], v[104:107]
	v_mfma_f32_16x16x32_bf16 v[92:95], v[144:147], v[198:201], v[92:95]
	v_mfma_f32_16x16x32_bf16 v[88:91], v[152:155], v[198:201], v[88:91]
	v_mfma_f32_16x16x32_bf16 v[76:79], v[144:147], v[206:209], v[76:79]
	v_mfma_f32_16x16x32_bf16 v[72:75], v[152:155], v[206:209], v[72:75]
	s_setprio 0
	s_setprio 1
	v_mfma_f32_16x16x32_bf16 v[116:119], v[156:159], v[172:175], v[116:119]
	v_mfma_f32_16x16x32_bf16 v[112:115], v[164:167], v[172:175], v[112:115]
	v_mfma_f32_16x16x32_bf16 v[100:103], v[156:159], v[186:189], v[100:103]
	v_mfma_f32_16x16x32_bf16 v[96:99], v[164:167], v[186:189], v[96:99]
	v_mfma_f32_16x16x32_bf16 v[84:87], v[156:159], v[194:197], v[84:87]
	v_mfma_f32_16x16x32_bf16 v[80:83], v[164:167], v[194:197], v[80:83]
	v_mfma_f32_16x16x32_bf16 v[68:71], v[156:159], v[202:205], v[68:71]
	v_mfma_f32_16x16x32_bf16 v[64:67], v[164:167], v[202:205], v[64:67]
	v_mfma_f32_16x16x32_bf16 v[116:119], v[160:163], v[176:179], v[116:119]
	v_mfma_f32_16x16x32_bf16 v[112:115], v[168:171], v[176:179], v[112:115]
	v_mfma_f32_16x16x32_bf16 v[100:103], v[160:163], v[190:193], v[100:103]
	v_mfma_f32_16x16x32_bf16 v[96:99], v[168:171], v[190:193], v[96:99]
	v_mfma_f32_16x16x32_bf16 v[84:87], v[160:163], v[198:201], v[84:87]
	v_mfma_f32_16x16x32_bf16 v[80:83], v[168:171], v[198:201], v[80:83]
	v_mfma_f32_16x16x32_bf16 v[68:71], v[160:163], v[206:209], v[68:71]
	v_mfma_f32_16x16x32_bf16 v[64:67], v[168:171], v[206:209], v[64:67]
	s_setprio 0
	s_barrier
	s_add_i32 s18, s41, s30
	v_lshl_add_u64 v[210:211], s[22:23], 0, v[128:129]
	s_mov_b32 m0, s18
	ds_read_b128 v[172:175], v184 offset:16384
	ds_read_b128 v[176:179], v184 offset:17408
	ds_read_b128 v[186:189], v184 offset:18432
	ds_read_b128 v[190:193], v184 offset:19456
	ds_read_b128 v[194:197], v184 offset:20480
	ds_read_b128 v[198:201], v184 offset:21504
	ds_read_b128 v[202:205], v184 offset:22528
	ds_read_b128 v[206:209], v184 offset:23552
	global_load_lds_dwordx4 v[210:211], off
	s_add_i32 m0, s18, 0x2000
	s_add_u32 s18, s22, 0xb0000
	v_lshl_add_u64 v[212:213], s[22:23], 0, v[130:131]
	s_addc_u32 s19, s23, 0
	s_add_i32 s52, s42, s30
	global_load_lds_dwordx4 v[212:213], off
	v_lshl_add_u64 v[214:215], s[18:19], 0, v[128:129]
	s_mov_b32 m0, s52
	v_lshl_add_u64 v[216:217], s[24:25], 0, v[130:131]
	global_load_lds_dwordx4 v[214:215], off
	v_lshl_add_u64 v[214:215], s[18:19], 0, v[130:131]
	s_add_i32 m0, s52, 0x2000
	s_nop 0
	global_load_lds_dwordx4 v[214:215], off
	v_lshl_add_u64 v[214:215], s[24:25], 0, v[128:129]
	s_mov_b32 m0, s31
	s_nop 0
	global_load_lds_dwordx4 v[214:215], off
	s_mov_b32 m0, s33
	s_nop 0
	global_load_lds_dwordx4 v[216:217], off
	s_waitcnt vmcnt(8)
	s_waitcnt lgkmcnt(0)
	s_barrier
	s_setprio 1
	s_waitcnt lgkmcnt(0)
	v_mfma_f32_16x16x32_bf16 v[60:63], v[140:143], v[172:175], v[60:63]
	v_mfma_f32_16x16x32_bf16 v[56:59], v[148:151], v[172:175], v[56:59]
	v_mfma_f32_16x16x32_bf16 v[44:47], v[140:143], v[186:189], v[44:47]
	v_mfma_f32_16x16x32_bf16 v[40:43], v[148:151], v[186:189], v[40:43]
	v_mfma_f32_16x16x32_bf16 v[28:31], v[140:143], v[194:197], v[28:31]
	v_mfma_f32_16x16x32_bf16 v[24:27], v[148:151], v[194:197], v[24:27]
	v_mfma_f32_16x16x32_bf16 v[12:15], v[140:143], v[202:205], v[12:15]
	v_mfma_f32_16x16x32_bf16 v[8:11], v[148:151], v[202:205], v[8:11]
	v_mfma_f32_16x16x32_bf16 v[60:63], v[144:147], v[176:179], v[60:63]
	v_mfma_f32_16x16x32_bf16 v[56:59], v[152:155], v[176:179], v[56:59]
	v_mfma_f32_16x16x32_bf16 v[44:47], v[144:147], v[190:193], v[44:47]
	v_mfma_f32_16x16x32_bf16 v[40:43], v[152:155], v[190:193], v[40:43]
	v_mfma_f32_16x16x32_bf16 v[28:31], v[144:147], v[198:201], v[28:31]
	v_mfma_f32_16x16x32_bf16 v[24:27], v[152:155], v[198:201], v[24:27]
	v_mfma_f32_16x16x32_bf16 v[12:15], v[144:147], v[206:209], v[12:15]
	v_mfma_f32_16x16x32_bf16 v[8:11], v[152:155], v[206:209], v[8:11]
	s_setprio 0
	s_setprio 1
	v_mfma_f32_16x16x32_bf16 v[52:55], v[156:159], v[172:175], v[52:55]
	v_mfma_f32_16x16x32_bf16 v[48:51], v[164:167], v[172:175], v[48:51]
	v_mfma_f32_16x16x32_bf16 v[36:39], v[156:159], v[186:189], v[36:39]
	v_mfma_f32_16x16x32_bf16 v[32:35], v[164:167], v[186:189], v[32:35]
	v_mfma_f32_16x16x32_bf16 v[20:23], v[156:159], v[194:197], v[20:23]
	v_mfma_f32_16x16x32_bf16 v[16:19], v[164:167], v[194:197], v[16:19]
	v_mfma_f32_16x16x32_bf16 v[4:7], v[156:159], v[202:205], v[4:7]
	v_mfma_f32_16x16x32_bf16 v[0:3], v[164:167], v[202:205], v[0:3]
	v_mfma_f32_16x16x32_bf16 v[52:55], v[160:163], v[176:179], v[52:55]
	v_mfma_f32_16x16x32_bf16 v[48:51], v[168:171], v[176:179], v[48:51]
	v_mfma_f32_16x16x32_bf16 v[36:39], v[160:163], v[190:193], v[36:39]
	v_mfma_f32_16x16x32_bf16 v[32:35], v[168:171], v[190:193], v[32:35]
	v_mfma_f32_16x16x32_bf16 v[20:23], v[160:163], v[198:201], v[20:23]
	v_mfma_f32_16x16x32_bf16 v[16:19], v[168:171], v[198:201], v[16:19]
	v_mfma_f32_16x16x32_bf16 v[4:7], v[160:163], v[206:209], v[4:7]
	v_mfma_f32_16x16x32_bf16 v[0:3], v[168:171], v[206:209], v[0:3]
	s_setprio 0
	s_barrier
	s_add_i32 s52, 0, 0x18000
	s_add_i32 s53, 0, 0x1c000
	v_add_u32_e32 v152, s52, v181
	v_add_u32_e32 v168, s53, v181
	ds_read_b128 v[140:143], v152
	ds_read_b128 v[144:147], v152 offset:1024
	ds_read_b128 v[148:151], v152 offset:2048
	ds_read_b128 v[152:155], v152 offset:3072
	ds_read_b128 v[156:159], v168
	ds_read_b128 v[160:163], v168 offset:1024
	ds_read_b128 v[164:167], v168 offset:2048
	ds_read_b128 v[168:171], v168 offset:3072
	s_add_u32 s18, s24, 0xb0000
	s_addc_u32 s19, s25, 0
	s_mov_b32 m0, s34
	v_lshl_add_u64 v[218:219], s[18:19], 0, v[128:129]
	ds_read_b128 v[172:175], v184 offset:32768
	ds_read_b128 v[176:179], v184 offset:33792
	ds_read_b128 v[186:189], v184 offset:34816
	ds_read_b128 v[190:193], v184 offset:35840
	ds_read_b128 v[194:197], v184 offset:36864
	ds_read_b128 v[198:201], v184 offset:37888
	ds_read_b128 v[202:205], v184 offset:38912
	ds_read_b128 v[206:209], v184 offset:39936
	global_load_lds_dwordx4 v[218:219], off
	v_lshl_add_u64 v[218:219], s[18:19], 0, v[130:131]
	s_mov_b32 m0, s35
	s_nop 0
	global_load_lds_dwordx4 v[218:219], off
	s_waitcnt vmcnt(8)
	s_waitcnt lgkmcnt(0)
	s_barrier
	s_setprio 1
	s_waitcnt lgkmcnt(0)
	v_mfma_f32_16x16x32_bf16 v[124:127], v[140:143], v[172:175], v[124:127]
	v_mfma_f32_16x16x32_bf16 v[120:123], v[148:151], v[172:175], v[120:123]
	v_mfma_f32_16x16x32_bf16 v[108:111], v[140:143], v[186:189], v[108:111]
	v_mfma_f32_16x16x32_bf16 v[104:107], v[148:151], v[186:189], v[104:107]
	v_mfma_f32_16x16x32_bf16 v[92:95], v[140:143], v[194:197], v[92:95]
	v_mfma_f32_16x16x32_bf16 v[88:91], v[148:151], v[194:197], v[88:91]
	v_mfma_f32_16x16x32_bf16 v[76:79], v[140:143], v[202:205], v[76:79]
	v_mfma_f32_16x16x32_bf16 v[72:75], v[148:151], v[202:205], v[72:75]
	v_mfma_f32_16x16x32_bf16 v[124:127], v[144:147], v[176:179], v[124:127]
	v_mfma_f32_16x16x32_bf16 v[120:123], v[152:155], v[176:179], v[120:123]
	v_mfma_f32_16x16x32_bf16 v[108:111], v[144:147], v[190:193], v[108:111]
	v_mfma_f32_16x16x32_bf16 v[104:107], v[152:155], v[190:193], v[104:107]
	v_mfma_f32_16x16x32_bf16 v[92:95], v[144:147], v[198:201], v[92:95]
	v_mfma_f32_16x16x32_bf16 v[88:91], v[152:155], v[198:201], v[88:91]
	v_mfma_f32_16x16x32_bf16 v[76:79], v[144:147], v[206:209], v[76:79]
	v_mfma_f32_16x16x32_bf16 v[72:75], v[152:155], v[206:209], v[72:75]
	s_setprio 0
	s_setprio 1
	v_mfma_f32_16x16x32_bf16 v[116:119], v[156:159], v[172:175], v[116:119]
	v_mfma_f32_16x16x32_bf16 v[112:115], v[164:167], v[172:175], v[112:115]
	v_mfma_f32_16x16x32_bf16 v[100:103], v[156:159], v[186:189], v[100:103]
	v_mfma_f32_16x16x32_bf16 v[96:99], v[164:167], v[186:189], v[96:99]
	v_mfma_f32_16x16x32_bf16 v[84:87], v[156:159], v[194:197], v[84:87]
	v_mfma_f32_16x16x32_bf16 v[80:83], v[164:167], v[194:197], v[80:83]
	v_mfma_f32_16x16x32_bf16 v[68:71], v[156:159], v[202:205], v[68:71]
	v_mfma_f32_16x16x32_bf16 v[64:67], v[164:167], v[202:205], v[64:67]
	v_mfma_f32_16x16x32_bf16 v[116:119], v[160:163], v[176:179], v[116:119]
	v_mfma_f32_16x16x32_bf16 v[112:115], v[168:171], v[176:179], v[112:115]
	v_mfma_f32_16x16x32_bf16 v[100:103], v[160:163], v[190:193], v[100:103]
	v_mfma_f32_16x16x32_bf16 v[96:99], v[168:171], v[190:193], v[96:99]
	v_mfma_f32_16x16x32_bf16 v[84:87], v[160:163], v[198:201], v[84:87]
	v_mfma_f32_16x16x32_bf16 v[80:83], v[168:171], v[198:201], v[80:83]
	v_mfma_f32_16x16x32_bf16 v[68:71], v[160:163], v[206:209], v[68:71]
	v_mfma_f32_16x16x32_bf16 v[64:67], v[168:171], v[206:209], v[64:67]
	s_setprio 0
	s_barrier
	s_add_i32 s18, s52, s30
	v_lshl_add_u64 v[210:211], v[210:211], 0, s[12:13]
	s_mov_b32 m0, s18
	ds_read_b128 v[172:175], v184 offset:49152
	ds_read_b128 v[176:179], v184 offset:50176
	ds_read_b128 v[186:189], v184 offset:51200
	ds_read_b128 v[190:193], v184 offset:52224
	ds_read_b128 v[194:197], v184 offset:53248
	ds_read_b128 v[198:201], v184 offset:54272
	ds_read_b128 v[202:205], v184 offset:55296
	ds_read_b128 v[206:209], v184 offset:56320
	global_load_lds_dwordx4 v[210:211], off
	s_add_i32 m0, s18, 0x2000
	s_add_u32 s18, s22, 0xb0080
	v_lshl_add_u64 v[210:211], v[212:213], 0, s[12:13]
	s_addc_u32 s19, s23, 0
	s_add_i32 s22, s53, s30
	global_load_lds_dwordx4 v[210:211], off
	v_lshl_add_u64 v[210:211], s[18:19], 0, v[128:129]
	s_mov_b32 m0, s22
	s_nop 0
	global_load_lds_dwordx4 v[210:211], off
	v_lshl_add_u64 v[210:211], s[18:19], 0, v[130:131]
	s_add_i32 m0, s22, 0x2000
	s_nop 0
	global_load_lds_dwordx4 v[210:211], off
	v_lshl_add_u64 v[210:211], v[214:215], 0, s[12:13]
	s_mov_b32 m0, s39
	s_nop 0
	global_load_lds_dwordx4 v[210:211], off
	v_lshl_add_u64 v[210:211], v[216:217], 0, s[12:13]
	s_mov_b32 m0, s40
	s_nop 0
	global_load_lds_dwordx4 v[210:211], off
	s_waitcnt vmcnt(8)
	s_waitcnt lgkmcnt(0)
	s_barrier
	s_setprio 1
	s_waitcnt lgkmcnt(0)
	v_mfma_f32_16x16x32_bf16 v[60:63], v[140:143], v[172:175], v[60:63]
	v_mfma_f32_16x16x32_bf16 v[56:59], v[148:151], v[172:175], v[56:59]
	v_mfma_f32_16x16x32_bf16 v[44:47], v[140:143], v[186:189], v[44:47]
	v_mfma_f32_16x16x32_bf16 v[40:43], v[148:151], v[186:189], v[40:43]
	v_mfma_f32_16x16x32_bf16 v[28:31], v[140:143], v[194:197], v[28:31]
	v_mfma_f32_16x16x32_bf16 v[24:27], v[148:151], v[194:197], v[24:27]
	v_mfma_f32_16x16x32_bf16 v[12:15], v[140:143], v[202:205], v[12:15]
	v_mfma_f32_16x16x32_bf16 v[8:11], v[148:151], v[202:205], v[8:11]
	v_mfma_f32_16x16x32_bf16 v[60:63], v[144:147], v[176:179], v[60:63]
	v_mfma_f32_16x16x32_bf16 v[56:59], v[152:155], v[176:179], v[56:59]
	v_mfma_f32_16x16x32_bf16 v[44:47], v[144:147], v[190:193], v[44:47]
	v_mfma_f32_16x16x32_bf16 v[40:43], v[152:155], v[190:193], v[40:43]
	v_mfma_f32_16x16x32_bf16 v[28:31], v[144:147], v[198:201], v[28:31]
	v_mfma_f32_16x16x32_bf16 v[24:27], v[152:155], v[198:201], v[24:27]
	v_mfma_f32_16x16x32_bf16 v[12:15], v[144:147], v[206:209], v[12:15]
	v_mfma_f32_16x16x32_bf16 v[8:11], v[152:155], v[206:209], v[8:11]
	s_setprio 0
	s_setprio 1
	v_mfma_f32_16x16x32_bf16 v[52:55], v[156:159], v[172:175], v[52:55]
	v_mfma_f32_16x16x32_bf16 v[48:51], v[164:167], v[172:175], v[48:51]
	v_mfma_f32_16x16x32_bf16 v[36:39], v[156:159], v[186:189], v[36:39]
	v_mfma_f32_16x16x32_bf16 v[32:35], v[164:167], v[186:189], v[32:35]
	v_mfma_f32_16x16x32_bf16 v[20:23], v[156:159], v[194:197], v[20:23]
	v_mfma_f32_16x16x32_bf16 v[16:19], v[164:167], v[194:197], v[16:19]
	v_mfma_f32_16x16x32_bf16 v[4:7], v[156:159], v[202:205], v[4:7]
	v_mfma_f32_16x16x32_bf16 v[0:3], v[164:167], v[202:205], v[0:3]
	v_mfma_f32_16x16x32_bf16 v[52:55], v[160:163], v[176:179], v[52:55]
	v_mfma_f32_16x16x32_bf16 v[48:51], v[168:171], v[176:179], v[48:51]
	v_mfma_f32_16x16x32_bf16 v[36:39], v[160:163], v[190:193], v[36:39]
	v_mfma_f32_16x16x32_bf16 v[32:35], v[168:171], v[190:193], v[32:35]
	v_mfma_f32_16x16x32_bf16 v[20:23], v[160:163], v[198:201], v[20:23]
	v_mfma_f32_16x16x32_bf16 v[16:19], v[168:171], v[198:201], v[16:19]
	v_mfma_f32_16x16x32_bf16 v[4:7], v[160:163], v[206:209], v[4:7]
	v_mfma_f32_16x16x32_bf16 v[0:3], v[168:171], v[206:209], v[0:3]
	s_setprio 0
	s_barrier
	s_add_i32 s51, s51, 2
	s_add_u32 s49, s49, 0x100
	s_addc_u32 s50, s50, 0
	s_cmp_gt_u32 s51, 41
	s_mov_b64 s[18:19], s[20:21]
	s_cbranch_scc0 .LBB0_1917
.Lqk_join_13:
	s_and_b64 vcc, exec, s[14:15]
	s_cbranch_vccz .LBB0_1920
	s_barrier
